# in_proj epilogues: per-row scale loads hoisted (silu, u), q/k row stores issued after the next row's loads so counted waits no longer drain stores
# speedup vs baseline: 1.0020x; 1.0020x over previous
; __device__ __forceinline__ unsigned pk2(float lo, float hi) { const f32x2c_t v = {lo, hi}; return __builtin_bit_cast(unsigned, __builtin_convertvector(v, bf16x2c_t)); }
;     __device__ __forceinline__ void operator()(const f32x4 (&acc)[2][2][4][2], const Unit& u, int wr, int wc, int fr, int fq) const {
;     ...
;         } else if (seg == 4) {
; #pragma unroll
;             for (int ai = 0; ai < 2; ++ai)
; #pragma unroll
;                 for (int m = 0; m < 4; ++m) {
;                     const int l = lbase + 128 * ai + 16 * m; const float rsv = rs[b * 2048 + l];
;                     const int c = l >> 4, t = l & 15;
; #pragma unroll
;                     for (int bj = 0; bj < 2; ++bj) {
;                         const int g = 16 * half + 4 * wc + 2 * bj + (fq >> 1);
;                         const f32x4 v0 = acc[ai][bj][m][0] * rsv, v1 = acc[ai][bj][m][1] * rsv;
;                         bf16_t* o = XU + ((size_t)(1024 * g + b * 128 + c)) * 384 + 128 + t * 16 + 8 * (fq & 1);
;                         *(u32x4*)o = (u32x4){pk2(v0[0], v0[1]), pk2(v0[2], v0[3]), pk2(v1[0], v1[1]), pk2(v1[2], v1[3])};
;                     }
;                 }
.LBB0_198:
	s_lshl_b32 s43, s39, 11
	v_add_u32_e32 v144, s43, v203
	v_ashrrev_i32_e32 v145, 31, v144
	v_lshl_add_u64 v[144:145], v[144:145], 2, s[20:21]
	global_load_dword v218, v[144:145], off
	global_load_dword v219, v[144:145], off offset:64
	global_load_dword v220, v[144:145], off offset:128
	global_load_dword v221, v[144:145], off offset:192
	global_load_dword v222, v[144:145], off offset:512
	global_load_dword v223, v[144:145], off offset:576
	global_load_dword v224, v[144:145], off offset:640
	global_load_dword v225, v[144:145], off offset:704
	s_lshl_b32 s42, s39, 7
	s_lshr_b32 s47, s47, 4
	v_lshl_or_b32 v162, s46, 14, v188
	v_or_b32_e32 v170, 16, v203
	s_add_i32 s47, s47, s42
	v_or_b32_e32 v171, 0x800, v162
	v_add_u32_e32 v146, s43, v170
	v_add_u32_e32 v145, s47, v162
	v_add_u32_e32 v148, s47, v171
	v_ashrrev_i32_e32 v147, 31, v146
	v_mad_i64_i32 v[154:155], s[62:63], v148, s55, v[138:139]
	v_lshl_add_u64 v[156:157], v[146:147], 2, s[20:21]
	v_mad_i64_i32 v[152:153], s[62:63], v145, s55, v[138:139]
	v_or_b32_e32 v172, 32, v203
	s_waitcnt vmcnt(0)
	v_mov_b32_e32 v144, v218
	v_pk_mul_f32 v[146:147], v[128:129], v[144:145] op_sel_hi:[1,0]
	v_pk_mul_f32 v[148:149], v[126:127], v[144:145] op_sel_hi:[1,0]
	v_pk_mul_f32 v[150:151], v[124:125], v[144:145] op_sel_hi:[1,0]
	v_pk_mul_f32 v[158:159], v[122:123], v[144:145] op_sel_hi:[1,0]
	v_pk_mul_f32 v[160:161], v[120:121], v[144:145] op_sel_hi:[1,0]
	v_pk_mul_f32 v[164:165], v[118:119], v[144:145] op_sel_hi:[1,0]
	v_pk_mul_f32 v[166:167], v[116:117], v[144:145] op_sel_hi:[1,0]
	v_pk_mul_f32 v[168:169], v[114:115], v[144:145] op_sel_hi:[1,0]
	v_cvt_pk_bf16_f32 v144, v148, v149
	v_cvt_pk_bf16_f32 v145, v146, v147
	v_cvt_pk_bf16_f32 v146, v158, v159
	v_cvt_pk_bf16_f32 v147, v150, v151
	v_cvt_pk_bf16_f32 v148, v164, v165
	v_cvt_pk_bf16_f32 v149, v160, v161
	v_cvt_pk_bf16_f32 v150, v168, v169
	v_cvt_pk_bf16_f32 v151, v166, v167
	global_store_dwordx4 v[152:153], v[144:147], off offset:256
	global_store_dwordx4 v[154:155], v[148:151], off offset:256
	v_lshrrev_b32_e32 v145, 4, v170
	v_add_u32_e32 v146, s43, v172
	v_add_u32_e32 v145, s42, v145
	v_ashrrev_i32_e32 v147, 31, v146
	v_add_u32_e32 v148, v145, v162
	v_add_u32_e32 v145, v145, v171
	v_lshl_add_u64 v[152:153], v[146:147], 2, s[20:21]
	v_mad_i64_i32 v[154:155], s[62:63], v148, s55, v[138:139]
	v_mad_i64_i32 v[156:157], s[62:63], v145, s55, v[138:139]
	v_or_b32_e32 v170, 48, v203
	v_mov_b32_e32 v144, v219
	v_pk_mul_f32 v[146:147], v[112:113], v[144:145] op_sel_hi:[1,0]
	v_pk_mul_f32 v[148:149], v[110:111], v[144:145] op_sel_hi:[1,0]
	v_pk_mul_f32 v[150:151], v[108:109], v[144:145] op_sel_hi:[1,0]
	v_pk_mul_f32 v[158:159], v[106:107], v[144:145] op_sel_hi:[1,0]
	v_pk_mul_f32 v[160:161], v[104:105], v[144:145] op_sel_hi:[1,0]
	v_pk_mul_f32 v[164:165], v[102:103], v[144:145] op_sel_hi:[1,0]
	v_pk_mul_f32 v[166:167], v[100:101], v[144:145] op_sel_hi:[1,0]
	v_pk_mul_f32 v[168:169], v[98:99], v[144:145] op_sel_hi:[1,0]
	v_cvt_pk_bf16_f32 v144, v148, v149
	v_cvt_pk_bf16_f32 v145, v146, v147
	v_cvt_pk_bf16_f32 v146, v158, v159
	v_cvt_pk_bf16_f32 v147, v150, v151
	v_cvt_pk_bf16_f32 v148, v164, v165
	v_cvt_pk_bf16_f32 v149, v160, v161
	v_cvt_pk_bf16_f32 v150, v168, v169
	v_cvt_pk_bf16_f32 v151, v166, v167
	global_store_dwordx4 v[154:155], v[144:147], off offset:256
	global_store_dwordx4 v[156:157], v[148:151], off offset:256
	v_lshrrev_b32_e32 v145, 4, v172
	v_add_u32_e32 v146, s43, v170
	v_add_u32_e32 v145, s42, v145
	v_ashrrev_i32_e32 v147, 31, v146
	v_add_u32_e32 v148, v145, v162
	v_add_u32_e32 v145, v145, v171
	v_lshl_add_u64 v[152:153], v[146:147], 2, s[20:21]
	v_mad_i64_i32 v[154:155], s[62:63], v148, s55, v[138:139]
	v_mad_i64_i32 v[156:157], s[62:63], v145, s55, v[138:139]
	v_add_u32_e32 v172, 0x80, v203
	v_mov_b32_e32 v144, v220
	v_pk_mul_f32 v[146:147], v[96:97], v[144:145] op_sel_hi:[1,0]
	v_pk_mul_f32 v[148:149], v[94:95], v[144:145] op_sel_hi:[1,0]
	v_pk_mul_f32 v[150:151], v[92:93], v[144:145] op_sel_hi:[1,0]
	v_pk_mul_f32 v[158:159], v[90:91], v[144:145] op_sel_hi:[1,0]
	v_pk_mul_f32 v[160:161], v[88:89], v[144:145] op_sel_hi:[1,0]
	v_pk_mul_f32 v[164:165], v[86:87], v[144:145] op_sel_hi:[1,0]
	v_pk_mul_f32 v[166:167], v[84:85], v[144:145] op_sel_hi:[1,0]
	v_pk_mul_f32 v[168:169], v[82:83], v[144:145] op_sel_hi:[1,0]
	v_cvt_pk_bf16_f32 v144, v148, v149
	v_cvt_pk_bf16_f32 v145, v146, v147
	v_cvt_pk_bf16_f32 v146, v158, v159
	v_cvt_pk_bf16_f32 v147, v150, v151
	v_cvt_pk_bf16_f32 v148, v164, v165
	v_cvt_pk_bf16_f32 v149, v160, v161
	v_cvt_pk_bf16_f32 v150, v168, v169
	v_cvt_pk_bf16_f32 v151, v166, v167
	global_store_dwordx4 v[154:155], v[144:147], off offset:256
	global_store_dwordx4 v[156:157], v[148:151], off offset:256
	v_lshrrev_b32_e32 v145, 4, v170
	v_add_u32_e32 v146, s43, v172
	v_add_u32_e32 v145, s42, v145
	v_ashrrev_i32_e32 v147, 31, v146
	v_add_u32_e32 v148, v145, v162
	v_add_u32_e32 v145, v145, v171
	v_lshl_add_u64 v[152:153], v[146:147], 2, s[20:21]
	v_mad_i64_i32 v[154:155], s[62:63], v148, s55, v[138:139]
	v_mad_i64_i32 v[156:157], s[62:63], v145, s55, v[138:139]
	v_add_u32_e32 v170, 0x90, v203
	v_mov_b32_e32 v144, v221
	v_pk_mul_f32 v[146:147], v[80:81], v[144:145] op_sel_hi:[1,0]
	v_pk_mul_f32 v[148:149], v[78:79], v[144:145] op_sel_hi:[1,0]
	v_pk_mul_f32 v[150:151], v[76:77], v[144:145] op_sel_hi:[1,0]
	v_pk_mul_f32 v[158:159], v[74:75], v[144:145] op_sel_hi:[1,0]
	v_pk_mul_f32 v[160:161], v[72:73], v[144:145] op_sel_hi:[1,0]
	v_pk_mul_f32 v[164:165], v[70:71], v[144:145] op_sel_hi:[1,0]
	v_pk_mul_f32 v[166:167], v[68:69], v[144:145] op_sel_hi:[1,0]
; __device__ __forceinline__ unsigned pk2(float lo, float hi) { const f32x2c_t v = {lo, hi}; return __builtin_bit_cast(unsigned, __builtin_convertvector(v, bf16x2c_t)); }
;     __device__ __forceinline__ void operator()(const f32x4 (&acc)[2][2][4][2], const Unit& u, int wr, int wc, int fr, int fq) const {
;     ...
;         } else if (seg == 4) {
; #pragma unroll
;             for (int ai = 0; ai < 2; ++ai)
; #pragma unroll
;                 for (int m = 0; m < 4; ++m) {
;                     const int l = lbase + 128 * ai + 16 * m; const float rsv = rs[b * 2048 + l];
;                     const int c = l >> 4, t = l & 15;
; #pragma unroll
;                     for (int bj = 0; bj < 2; ++bj) {
;                         const int g = 16 * half + 4 * wc + 2 * bj + (fq >> 1);
;                         const f32x4 v0 = acc[ai][bj][m][0] * rsv, v1 = acc[ai][bj][m][1] * rsv;
;                         bf16_t* o = XU + ((size_t)(1024 * g + b * 128 + c)) * 384 + 128 + t * 16 + 8 * (fq & 1);
;                         *(u32x4*)o = (u32x4){pk2(v0[0], v0[1]), pk2(v0[2], v0[3]), pk2(v1[0], v1[1]), pk2(v1[2], v1[3])};
;                     }
;                 }
	v_pk_mul_f32 v[168:169], v[66:67], v[144:145] op_sel_hi:[1,0]
	v_cvt_pk_bf16_f32 v144, v148, v149
	v_cvt_pk_bf16_f32 v145, v146, v147
	v_cvt_pk_bf16_f32 v146, v158, v159
	v_cvt_pk_bf16_f32 v147, v150, v151
	v_cvt_pk_bf16_f32 v148, v164, v165
	v_cvt_pk_bf16_f32 v149, v160, v161
	v_cvt_pk_bf16_f32 v150, v168, v169
	v_cvt_pk_bf16_f32 v151, v166, v167
	global_store_dwordx4 v[154:155], v[144:147], off offset:256
	global_store_dwordx4 v[156:157], v[148:151], off offset:256
	v_lshrrev_b32_e32 v145, 4, v172
	v_add_u32_e32 v146, s43, v170
	v_add_u32_e32 v145, s42, v145
	v_ashrrev_i32_e32 v147, 31, v146
	v_add_u32_e32 v148, v145, v162
	v_add_u32_e32 v145, v145, v171
	v_lshl_add_u64 v[152:153], v[146:147], 2, s[20:21]
	v_mad_i64_i32 v[154:155], s[62:63], v148, s55, v[138:139]
	v_mad_i64_i32 v[156:157], s[62:63], v145, s55, v[138:139]
	v_add_u32_e32 v172, 0xa0, v203
	v_mov_b32_e32 v144, v222
	v_pk_mul_f32 v[146:147], v[64:65], v[144:145] op_sel_hi:[1,0]
	v_pk_mul_f32 v[148:149], v[62:63], v[144:145] op_sel_hi:[1,0]
	v_pk_mul_f32 v[150:151], v[60:61], v[144:145] op_sel_hi:[1,0]
	v_pk_mul_f32 v[158:159], v[58:59], v[144:145] op_sel_hi:[1,0]
	v_pk_mul_f32 v[160:161], v[56:57], v[144:145] op_sel_hi:[1,0]
	v_pk_mul_f32 v[164:165], v[54:55], v[144:145] op_sel_hi:[1,0]
	v_pk_mul_f32 v[166:167], v[52:53], v[144:145] op_sel_hi:[1,0]
	v_pk_mul_f32 v[168:169], v[50:51], v[144:145] op_sel_hi:[1,0]
	v_cvt_pk_bf16_f32 v144, v148, v149
	v_cvt_pk_bf16_f32 v145, v146, v147
	v_cvt_pk_bf16_f32 v146, v158, v159
	v_cvt_pk_bf16_f32 v147, v150, v151
	v_cvt_pk_bf16_f32 v148, v164, v165
	v_cvt_pk_bf16_f32 v149, v160, v161
	v_cvt_pk_bf16_f32 v150, v168, v169
	v_cvt_pk_bf16_f32 v151, v166, v167
	global_store_dwordx4 v[154:155], v[144:147], off offset:256
	global_store_dwordx4 v[156:157], v[148:151], off offset:256
	v_lshrrev_b32_e32 v145, 4, v170
	v_add_u32_e32 v146, s43, v172
	v_add_u32_e32 v145, s42, v145
	v_ashrrev_i32_e32 v147, 31, v146
	v_add_u32_e32 v148, v145, v162
	v_add_u32_e32 v145, v145, v171
	v_lshl_add_u64 v[152:153], v[146:147], 2, s[20:21]
	v_mad_i64_i32 v[154:155], s[62:63], v148, s55, v[138:139]
	v_mad_i64_i32 v[156:157], s[62:63], v145, s55, v[138:139]
	v_add_u32_e32 v170, 0xb0, v203
	v_mov_b32_e32 v144, v223
	v_pk_mul_f32 v[146:147], v[48:49], v[144:145] op_sel_hi:[1,0]
	v_pk_mul_f32 v[148:149], v[46:47], v[144:145] op_sel_hi:[1,0]
	v_pk_mul_f32 v[150:151], v[44:45], v[144:145] op_sel_hi:[1,0]
	v_pk_mul_f32 v[158:159], v[42:43], v[144:145] op_sel_hi:[1,0]
	v_pk_mul_f32 v[160:161], v[40:41], v[144:145] op_sel_hi:[1,0]
	v_pk_mul_f32 v[164:165], v[38:39], v[144:145] op_sel_hi:[1,0]
	v_pk_mul_f32 v[166:167], v[36:37], v[144:145] op_sel_hi:[1,0]
	v_pk_mul_f32 v[168:169], v[34:35], v[144:145] op_sel_hi:[1,0]
	v_cvt_pk_bf16_f32 v144, v148, v149
	v_cvt_pk_bf16_f32 v145, v146, v147
	v_cvt_pk_bf16_f32 v146, v158, v159
	v_cvt_pk_bf16_f32 v147, v150, v151
	v_cvt_pk_bf16_f32 v148, v164, v165
	v_cvt_pk_bf16_f32 v149, v160, v161
	v_cvt_pk_bf16_f32 v150, v168, v169
	v_cvt_pk_bf16_f32 v151, v166, v167
	global_store_dwordx4 v[154:155], v[144:147], off offset:256
	global_store_dwordx4 v[156:157], v[148:151], off offset:256
	v_lshrrev_b32_e32 v145, 4, v172
	v_add_u32_e32 v146, s43, v170
	v_add_u32_e32 v145, s42, v145
	v_ashrrev_i32_e32 v147, 31, v146
	v_add_u32_e32 v148, v145, v162
	v_add_u32_e32 v145, v145, v171
	v_lshl_add_u64 v[152:153], v[146:147], 2, s[20:21]
	v_mad_i64_i32 v[154:155], s[62:63], v148, s55, v[138:139]
	v_mad_i64_i32 v[156:157], s[62:63], v145, s55, v[138:139]
	v_mov_b32_e32 v144, v224
	v_pk_mul_f32 v[146:147], v[32:33], v[144:145] op_sel_hi:[1,0]
	v_pk_mul_f32 v[148:149], v[30:31], v[144:145] op_sel_hi:[1,0]
	v_pk_mul_f32 v[150:151], v[28:29], v[144:145] op_sel_hi:[1,0]
	v_pk_mul_f32 v[158:159], v[26:27], v[144:145] op_sel_hi:[1,0]
	v_pk_mul_f32 v[160:161], v[24:25], v[144:145] op_sel_hi:[1,0]
	v_pk_mul_f32 v[164:165], v[22:23], v[144:145] op_sel_hi:[1,0]
	v_pk_mul_f32 v[166:167], v[20:21], v[144:145] op_sel_hi:[1,0]
	v_pk_mul_f32 v[168:169], v[18:19], v[144:145] op_sel_hi:[1,0]
	v_cvt_pk_bf16_f32 v144, v148, v149
	v_cvt_pk_bf16_f32 v145, v146, v147
	v_cvt_pk_bf16_f32 v146, v158, v159
	v_cvt_pk_bf16_f32 v147, v150, v151
	v_cvt_pk_bf16_f32 v148, v164, v165
	v_cvt_pk_bf16_f32 v149, v160, v161
	v_cvt_pk_bf16_f32 v150, v168, v169
	v_cvt_pk_bf16_f32 v151, v166, v167
	global_store_dwordx4 v[154:155], v[144:147], off offset:256
	global_store_dwordx4 v[156:157], v[148:151], off offset:256
	v_lshrrev_b32_e32 v145, 4, v170
	v_add_u32_e32 v145, s42, v145
	v_add_u32_e32 v146, v145, v162
	v_add_u32_e32 v145, v145, v171
	v_mad_i64_i32 v[152:153], s[42:43], v146, s55, v[138:139]
	v_mad_i64_i32 v[154:155], s[42:43], v145, s55, v[138:139]
	v_mov_b32_e32 v144, v225
	v_pk_mul_f32 v[146:147], v[16:17], v[144:145] op_sel_hi:[1,0]
	v_pk_mul_f32 v[148:149], v[14:15], v[144:145] op_sel_hi:[1,0]
	v_pk_mul_f32 v[150:151], v[12:13], v[144:145] op_sel_hi:[1,0]
	v_pk_mul_f32 v[156:157], v[10:11], v[144:145] op_sel_hi:[1,0]
	v_pk_mul_f32 v[158:159], v[8:9], v[144:145] op_sel_hi:[1,0]
	v_pk_mul_f32 v[160:161], v[6:7], v[144:145] op_sel_hi:[1,0]
	v_pk_mul_f32 v[164:165], v[4:5], v[144:145] op_sel_hi:[1,0]
	v_pk_mul_f32 v[166:167], v[2:3], v[144:145] op_sel_hi:[1,0]
	v_cvt_pk_bf16_f32 v144, v148, v149
	v_cvt_pk_bf16_f32 v145, v146, v147
	v_cvt_pk_bf16_f32 v146, v156, v157
	v_cvt_pk_bf16_f32 v147, v150, v151
	v_cvt_pk_bf16_f32 v148, v160, v161
	v_cvt_pk_bf16_f32 v149, v158, v159
	v_cvt_pk_bf16_f32 v150, v166, v167
	v_cvt_pk_bf16_f32 v151, v164, v165
	global_store_dwordx4 v[152:153], v[144:147], off offset:256
	global_store_dwordx4 v[154:155], v[148:151], off offset:256

; __device__ __forceinline__ unsigned pk2(float lo, float hi) { const f32x2c_t v = {lo, hi}; return __builtin_bit_cast(unsigned, __builtin_convertvector(v, bf16x2c_t)); }
; __device__ __forceinline__ float siluf_(float v) { return v * sigmoidf_(v); }
;     __device__ __forceinline__ void operator()(const f32x4 (&acc)[2][2][4][2], const Unit& u, int wr, int wc, int fr, int fq) const {
;     ...
;         } else {
;             bf16_t* dst = seg == 3 ? SZA : SZS;
; #pragma unroll
;             for (int ai = 0; ai < 2; ++ai)
; #pragma unroll
;                 for (int m = 0; m < 4; ++m) {
;                     const int l = lbase + 128 * ai + 16 * m; const int row = b * 2048 + l; const float rsv = rs[row];
; #pragma unroll
;                     for (int bj = 0; bj < 2; ++bj) {
;                         const int col = 256 * half + 64 * wc + 32 * bj + 8 * fq;
;                         const f32x4 v0 = acc[ai][bj][m][0] * rsv, v1 = acc[ai][bj][m][1] * rsv;
;                         *(u32x4*)(dst + (size_t)row * 512 + col) = (u32x4){pk2(siluf_(v0[0]), siluf_(v0[1])), pk2(siluf_(v0[2]), siluf_(v0[3])), pk2(siluf_(v1[0]), siluf_(v1[1])), pk2(siluf_(v1[2]), siluf_(v1[3]))};
;                     }
;                 }
;         }
.LBB0_200:
	s_and_b64 vcc, exec, s[44:45]
	s_cbranch_vccz .LBB0_202
	v_lshl_add_u32 v144, s39, 11, v203
	v_ashrrev_i32_e32 v145, 31, v144
	v_lshl_add_u64 v[146:147], v[144:145], 2, s[20:21]
	global_load_dword v218, v[146:147], off
	global_load_dword v219, v[146:147], off offset:64
	global_load_dword v220, v[146:147], off offset:128
	global_load_dword v221, v[146:147], off offset:192
	global_load_dword v222, v[146:147], off offset:512
	global_load_dword v223, v[146:147], off offset:576
	global_load_dword v224, v[146:147], off offset:640
	global_load_dword v225, v[146:147], off offset:704
	v_lshlrev_b64 v[150:151], 10, v[144:145]
	v_lshl_or_b32 v146, s46, 9, v192
	v_mov_b32_e32 v147, v131
	v_lshl_add_u64 v[150:151], s[42:43], 0, v[150:151]
	v_lshl_add_u64 v[156:157], v[150:151], 0, v[146:147]
	s_waitcnt vmcnt(0)
	v_mov_b32_e32 v148, v218
	v_pk_mul_f32 v[150:151], v[128:129], v[148:149] op_sel_hi:[1,0]
	v_pk_mul_f32 v[152:153], v[126:127], v[148:149] op_sel_hi:[1,0]
	v_pk_mul_f32 v[154:155], v[124:125], v[148:149] op_sel_hi:[1,0]
	v_pk_mul_f32 v[158:159], v[122:123], v[148:149] op_sel_hi:[1,0]
	v_pk_mul_f32 v[160:161], v[120:121], v[148:149] op_sel_hi:[1,0]
	v_pk_mul_f32 v[164:165], v[118:119], v[148:149] op_sel_hi:[1,0]
	v_pk_mul_f32 v[166:167], v[116:117], v[148:149] op_sel_hi:[1,0]
	v_pk_mul_f32 v[148:149], v[114:115], v[148:149] op_sel_hi:[1,0]
	v_mul_f32_e32 v145, 0xbfb8aa3b, v152
	v_mul_f32_e32 v162, 0xbfb8aa3b, v153
	v_mul_f32_e32 v168, 0xbfb8aa3b, v150
	v_mul_f32_e32 v169, 0xbfb8aa3b, v151
	v_mul_f32_e32 v170, 0xbfb8aa3b, v158
	v_mul_f32_e32 v171, 0xbfb8aa3b, v159
	v_mul_f32_e32 v172, 0xbfb8aa3b, v154
	v_mul_f32_e32 v173, 0xbfb8aa3b, v155
	v_mul_f32_e32 v174, 0xbfb8aa3b, v164
	v_mul_f32_e32 v175, 0xbfb8aa3b, v165
	v_mul_f32_e32 v178, 0xbfb8aa3b, v148
	v_mul_f32_e32 v179, 0xbfb8aa3b, v149
	v_exp_f32_e32 v145, v145
	v_exp_f32_e32 v162, v162
	v_exp_f32_e32 v168, v168
	v_exp_f32_e32 v169, v169
	v_exp_f32_e32 v170, v170
	v_exp_f32_e32 v171, v171
	v_exp_f32_e32 v172, v172
	v_exp_f32_e32 v173, v173
	v_mul_f32_e32 v176, 0xbfb8aa3b, v160
	v_mul_f32_e32 v177, 0xbfb8aa3b, v161
	v_mul_f32_e32 v180, 0xbfb8aa3b, v166
	v_mul_f32_e32 v181, 0xbfb8aa3b, v167
	v_exp_f32_e32 v174, v174
	v_exp_f32_e32 v175, v175
	v_exp_f32_e32 v178, v178
	v_exp_f32_e32 v179, v179
	v_exp_f32_e32 v176, v176
	v_exp_f32_e32 v177, v177
	v_exp_f32_e32 v180, v180
	v_exp_f32_e32 v181, v181
	v_add_f32_e32 v145, 1.0, v145
	v_add_f32_e32 v162, 1.0, v162
	v_add_f32_e32 v182, 1.0, v168
	v_add_f32_e32 v183, 1.0, v169
	v_add_f32_e32 v184, 1.0, v170
	v_add_f32_e32 v185, 1.0, v171
	v_add_f32_e32 v204, 1.0, v172
	v_add_f32_e32 v205, 1.0, v173
	v_add_f32_e32 v208, 1.0, v174
	v_add_f32_e32 v209, 1.0, v175
	v_add_f32_e32 v214, 1.0, v178
	v_add_f32_e32 v215, 1.0, v179
	v_rcp_f32_e32 v168, v145
	v_rcp_f32_e32 v169, v162
	v_rcp_f32_e32 v170, v182
	v_rcp_f32_e32 v171, v183
	v_rcp_f32_e32 v172, v184
	v_rcp_f32_e32 v173, v185
	v_rcp_f32_e32 v174, v204
	v_rcp_f32_e32 v175, v205
	v_add_f32_e32 v210, 1.0, v176
	v_add_f32_e32 v211, 1.0, v177
	v_add_f32_e32 v216, 1.0, v180
	v_add_f32_e32 v217, 1.0, v181
	v_rcp_f32_e32 v180, v214
	v_rcp_f32_e32 v181, v215
	v_rcp_f32_e32 v176, v208
	v_rcp_f32_e32 v177, v209
	v_rcp_f32_e32 v178, v210
	v_rcp_f32_e32 v179, v211
	v_rcp_f32_e32 v182, v216
	v_rcp_f32_e32 v183, v217
	v_pk_mul_f32 v[152:153], v[152:153], v[168:169]
	v_pk_mul_f32 v[150:151], v[150:151], v[170:171]
	v_pk_mul_f32 v[158:159], v[158:159], v[172:173]
	v_pk_mul_f32 v[154:155], v[154:155], v[174:175]
	v_pk_mul_f32 v[168:169], v[148:149], v[180:181]
	v_cvt_pk_bf16_f32 v148, v152, v153
	v_cvt_pk_bf16_f32 v149, v150, v151
	v_cvt_pk_bf16_f32 v150, v158, v159
	v_cvt_pk_bf16_f32 v151, v154, v155
	v_pk_mul_f32 v[164:165], v[164:165], v[176:177]
	v_pk_mul_f32 v[160:161], v[160:161], v[178:179]
	v_pk_mul_f32 v[166:167], v[166:167], v[182:183]
	global_store_dwordx4 v[156:157], v[148:151], off
	v_cvt_pk_bf16_f32 v152, v164, v165
	v_cvt_pk_bf16_f32 v153, v160, v161
	v_or_b32_e32 v148, 16, v144
	v_cvt_pk_bf16_f32 v154, v168, v169
	v_cvt_pk_bf16_f32 v155, v166, v167
	v_ashrrev_i32_e32 v149, 31, v148
	global_store_dwordx4 v[156:157], v[152:155], off offset:64
	v_lshl_add_u64 v[150:151], v[148:149], 2, s[20:21]
	v_mov_b32_e32 v150, v219
	v_lshlrev_b64 v[148:149], 10, v[148:149]
	v_lshl_add_u64 v[148:149], s[42:43], 0, v[148:149]
	v_lshl_add_u64 v[156:157], v[148:149], 0, v[146:147]
	v_pk_mul_f32 v[148:149], v[112:113], v[150:151] op_sel_hi:[1,0]
	v_pk_mul_f32 v[152:153], v[110:111], v[150:151] op_sel_hi:[1,0]
	v_pk_mul_f32 v[154:155], v[108:109], v[150:151] op_sel_hi:[1,0]
	v_pk_mul_f32 v[158:159], v[106:107], v[150:151] op_sel_hi:[1,0]
	v_pk_mul_f32 v[160:161], v[104:105], v[150:151] op_sel_hi:[1,0]
	v_pk_mul_f32 v[164:165], v[102:103], v[150:151] op_sel_hi:[1,0]
	v_pk_mul_f32 v[166:167], v[100:101], v[150:151] op_sel_hi:[1,0]
	v_pk_mul_f32 v[168:169], v[98:99], v[150:151] op_sel_hi:[1,0]
	v_mul_f32_e32 v145, 0xbfb8aa3b, v152
	v_mul_f32_e32 v150, 0xbfb8aa3b, v153
	v_mul_f32_e32 v151, 0xbfb8aa3b, v148
	v_mul_f32_e32 v162, 0xbfb8aa3b, v149
	v_mul_f32_e32 v170, 0xbfb8aa3b, v158
	v_mul_f32_e32 v171, 0xbfb8aa3b, v159
	v_mul_f32_e32 v172, 0xbfb8aa3b, v154
	v_mul_f32_e32 v173, 0xbfb8aa3b, v155
	v_mul_f32_e32 v174, 0xbfb8aa3b, v164
	v_mul_f32_e32 v175, 0xbfb8aa3b, v165
	v_exp_f32_e32 v145, v145
	v_exp_f32_e32 v150, v150
	v_exp_f32_e32 v151, v151
	v_exp_f32_e32 v162, v162
	v_exp_f32_e32 v170, v170
	v_exp_f32_e32 v171, v171
	v_exp_f32_e32 v172, v172
	v_exp_f32_e32 v173, v173
	v_mul_f32_e32 v178, 0xbfb8aa3b, v168
	v_mul_f32_e32 v179, 0xbfb8aa3b, v169
	v_exp_f32_e32 v174, v174
	v_exp_f32_e32 v175, v175
	v_mul_f32_e32 v180, 0xbfb8aa3b, v166
; __device__ __forceinline__ unsigned pk2(float lo, float hi) { const f32x2c_t v = {lo, hi}; return __builtin_bit_cast(unsigned, __builtin_convertvector(v, bf16x2c_t)); }
; __device__ __forceinline__ float siluf_(float v) { return v * sigmoidf_(v); }
;     __device__ __forceinline__ void operator()(const f32x4 (&acc)[2][2][4][2], const Unit& u, int wr, int wc, int fr, int fq) const {
;     ...
;         } else {
;             bf16_t* dst = seg == 3 ? SZA : SZS;
; #pragma unroll
;             for (int ai = 0; ai < 2; ++ai)
; #pragma unroll
;                 for (int m = 0; m < 4; ++m) {
;                     const int l = lbase + 128 * ai + 16 * m; const int row = b * 2048 + l; const float rsv = rs[row];
; #pragma unroll
;                     for (int bj = 0; bj < 2; ++bj) {
;                         const int col = 256 * half + 64 * wc + 32 * bj + 8 * fq;
;                         const f32x4 v0 = acc[ai][bj][m][0] * rsv, v1 = acc[ai][bj][m][1] * rsv;
;                         *(u32x4*)(dst + (size_t)row * 512 + col) = (u32x4){pk2(siluf_(v0[0]), siluf_(v0[1])), pk2(siluf_(v0[2]), siluf_(v0[3])), pk2(siluf_(v1[0]), siluf_(v1[1])), pk2(siluf_(v1[2]), siluf_(v1[3]))};
;                     }
;                 }
;         }
	v_mul_f32_e32 v181, 0xbfb8aa3b, v167
	v_exp_f32_e32 v178, v178
	v_exp_f32_e32 v179, v179
	v_mul_f32_e32 v176, 0xbfb8aa3b, v160
	v_mul_f32_e32 v177, 0xbfb8aa3b, v161
	v_exp_f32_e32 v180, v180
	v_exp_f32_e32 v181, v181
	v_exp_f32_e32 v176, v176
	v_exp_f32_e32 v177, v177
	v_add_f32_e32 v145, 1.0, v145
	v_add_f32_e32 v182, 1.0, v150
	v_add_f32_e32 v183, 1.0, v151
	v_add_f32_e32 v162, 1.0, v162
	v_add_f32_e32 v184, 1.0, v170
	v_add_f32_e32 v185, 1.0, v171
	v_add_f32_e32 v204, 1.0, v172
	v_add_f32_e32 v205, 1.0, v173
	v_add_f32_e32 v208, 1.0, v174
	v_add_f32_e32 v209, 1.0, v175
	v_rcp_f32_e32 v150, v145
	v_rcp_f32_e32 v151, v182
	v_rcp_f32_e32 v170, v183
	v_rcp_f32_e32 v171, v162
	v_rcp_f32_e32 v172, v184
	v_rcp_f32_e32 v173, v185
	v_rcp_f32_e32 v174, v204
	v_rcp_f32_e32 v175, v205
	v_add_f32_e32 v214, 1.0, v178
	v_add_f32_e32 v215, 1.0, v179
	v_add_f32_e32 v216, 1.0, v180
	v_add_f32_e32 v217, 1.0, v181
	v_rcp_f32_e32 v180, v214
	v_rcp_f32_e32 v181, v215
	v_add_f32_e32 v210, 1.0, v176
	v_add_f32_e32 v211, 1.0, v177
	v_rcp_f32_e32 v182, v216
	v_rcp_f32_e32 v183, v217
	v_rcp_f32_e32 v176, v208
	v_rcp_f32_e32 v177, v209
	v_rcp_f32_e32 v178, v210
	v_rcp_f32_e32 v179, v211
	v_pk_mul_f32 v[150:151], v[152:153], v[150:151]
	v_pk_mul_f32 v[152:153], v[148:149], v[170:171]
	v_pk_mul_f32 v[158:159], v[158:159], v[172:173]
	v_pk_mul_f32 v[154:155], v[154:155], v[174:175]
	v_cvt_pk_bf16_f32 v148, v150, v151
	v_cvt_pk_bf16_f32 v149, v152, v153
	v_cvt_pk_bf16_f32 v150, v158, v159
	v_cvt_pk_bf16_f32 v151, v154, v155
	global_store_dwordx4 v[156:157], v[148:151], off
	v_pk_mul_f32 v[164:165], v[164:165], v[176:177]
	v_pk_mul_f32 v[160:161], v[160:161], v[178:179]
	v_pk_mul_f32 v[148:149], v[168:169], v[180:181]
	v_cvt_pk_bf16_f32 v152, v164, v165
	v_cvt_pk_bf16_f32 v154, v148, v149
	v_pk_mul_f32 v[148:149], v[166:167], v[182:183]
	v_cvt_pk_bf16_f32 v153, v160, v161
	v_cvt_pk_bf16_f32 v155, v148, v149
	v_or_b32_e32 v148, 32, v144
	v_ashrrev_i32_e32 v149, 31, v148
	global_store_dwordx4 v[156:157], v[152:155], off offset:64
	v_lshl_add_u64 v[150:151], v[148:149], 2, s[20:21]
	v_mov_b32_e32 v150, v220
	v_lshlrev_b64 v[148:149], 10, v[148:149]
	v_lshl_add_u64 v[148:149], s[42:43], 0, v[148:149]
	v_lshl_add_u64 v[156:157], v[148:149], 0, v[146:147]
	v_pk_mul_f32 v[148:149], v[96:97], v[150:151] op_sel_hi:[1,0]
	v_pk_mul_f32 v[152:153], v[94:95], v[150:151] op_sel_hi:[1,0]
	v_pk_mul_f32 v[154:155], v[92:93], v[150:151] op_sel_hi:[1,0]
	v_pk_mul_f32 v[158:159], v[90:91], v[150:151] op_sel_hi:[1,0]
	v_pk_mul_f32 v[160:161], v[88:89], v[150:151] op_sel_hi:[1,0]
	v_pk_mul_f32 v[164:165], v[86:87], v[150:151] op_sel_hi:[1,0]
	v_pk_mul_f32 v[166:167], v[84:85], v[150:151] op_sel_hi:[1,0]
	v_pk_mul_f32 v[168:169], v[82:83], v[150:151] op_sel_hi:[1,0]
	v_mul_f32_e32 v145, 0xbfb8aa3b, v152
	v_mul_f32_e32 v150, 0xbfb8aa3b, v153
	v_mul_f32_e32 v151, 0xbfb8aa3b, v148
	v_mul_f32_e32 v162, 0xbfb8aa3b, v149
	v_mul_f32_e32 v170, 0xbfb8aa3b, v158
	v_mul_f32_e32 v171, 0xbfb8aa3b, v159
	v_mul_f32_e32 v172, 0xbfb8aa3b, v154
	v_mul_f32_e32 v173, 0xbfb8aa3b, v155
	v_mul_f32_e32 v174, 0xbfb8aa3b, v164
	v_mul_f32_e32 v175, 0xbfb8aa3b, v165
	v_exp_f32_e32 v145, v145
	v_exp_f32_e32 v150, v150
	v_exp_f32_e32 v151, v151
	v_exp_f32_e32 v162, v162
	v_exp_f32_e32 v170, v170
	v_exp_f32_e32 v171, v171
	v_exp_f32_e32 v172, v172
	v_exp_f32_e32 v173, v173
	v_mul_f32_e32 v178, 0xbfb8aa3b, v168
	v_mul_f32_e32 v179, 0xbfb8aa3b, v169
	v_exp_f32_e32 v174, v174
	v_exp_f32_e32 v175, v175
	v_mul_f32_e32 v180, 0xbfb8aa3b, v166
	v_mul_f32_e32 v181, 0xbfb8aa3b, v167
	v_exp_f32_e32 v178, v178
	v_exp_f32_e32 v179, v179
	v_mul_f32_e32 v176, 0xbfb8aa3b, v160
	v_mul_f32_e32 v177, 0xbfb8aa3b, v161
	v_exp_f32_e32 v180, v180
	v_exp_f32_e32 v183, v181
	v_exp_f32_e32 v176, v176
	v_exp_f32_e32 v177, v177
	v_add_f32_e32 v145, 1.0, v145
	v_add_f32_e32 v181, 1.0, v150
	v_add_f32_e32 v182, 1.0, v151
	v_add_f32_e32 v162, 1.0, v162
	v_add_f32_e32 v184, 1.0, v170
	v_add_f32_e32 v185, 1.0, v171
	v_add_f32_e32 v204, 1.0, v172
	v_add_f32_e32 v205, 1.0, v173
	v_add_f32_e32 v208, 1.0, v174
	v_add_f32_e32 v209, 1.0, v175
	v_rcp_f32_e32 v150, v145
	v_rcp_f32_e32 v151, v181
	v_rcp_f32_e32 v170, v182
	v_rcp_f32_e32 v171, v162
	v_rcp_f32_e32 v172, v184
	v_rcp_f32_e32 v173, v185
	v_rcp_f32_e32 v174, v204
	v_rcp_f32_e32 v175, v205
	v_add_f32_e32 v214, 1.0, v178
	v_add_f32_e32 v215, 1.0, v179
	v_add_f32_e32 v216, 1.0, v180
	v_rcp_f32_e32 v180, v214
	v_rcp_f32_e32 v181, v215
	v_add_f32_e32 v145, 1.0, v183
	v_add_f32_e32 v210, 1.0, v176
	v_add_f32_e32 v211, 1.0, v177
	v_rcp_f32_e32 v182, v216
	v_rcp_f32_e32 v183, v145
	v_rcp_f32_e32 v176, v208
	v_rcp_f32_e32 v177, v209
	v_rcp_f32_e32 v178, v210
	v_rcp_f32_e32 v179, v211
	v_pk_mul_f32 v[150:151], v[152:153], v[150:151]
	v_pk_mul_f32 v[152:153], v[148:149], v[170:171]
	v_pk_mul_f32 v[158:159], v[158:159], v[172:173]
	v_pk_mul_f32 v[154:155], v[154:155], v[174:175]
	v_cvt_pk_bf16_f32 v148, v150, v151
	v_cvt_pk_bf16_f32 v149, v152, v153
	v_cvt_pk_bf16_f32 v150, v158, v159
	v_cvt_pk_bf16_f32 v151, v154, v155
	global_store_dwordx4 v[156:157], v[148:151], off
	v_pk_mul_f32 v[164:165], v[164:165], v[176:177]
	v_pk_mul_f32 v[160:161], v[160:161], v[178:179]
	v_pk_mul_f32 v[148:149], v[168:169], v[180:181]
	v_cvt_pk_bf16_f32 v152, v164, v165
	v_cvt_pk_bf16_f32 v154, v148, v149
	v_pk_mul_f32 v[148:149], v[166:167], v[182:183]
	v_cvt_pk_bf16_f32 v153, v160, v161
	v_cvt_pk_bf16_f32 v155, v148, v149
	v_or_b32_e32 v148, 48, v144
	v_ashrrev_i32_e32 v149, 31, v148
	global_store_dwordx4 v[156:157], v[152:155], off offset:64
	v_lshl_add_u64 v[150:151], v[148:149], 2, s[20:21]
	v_mov_b32_e32 v150, v221
; __device__ __forceinline__ unsigned pk2(float lo, float hi) { const f32x2c_t v = {lo, hi}; return __builtin_bit_cast(unsigned, __builtin_convertvector(v, bf16x2c_t)); }
; __device__ __forceinline__ float siluf_(float v) { return v * sigmoidf_(v); }
;     __device__ __forceinline__ void operator()(const f32x4 (&acc)[2][2][4][2], const Unit& u, int wr, int wc, int fr, int fq) const {
;     ...
;         } else {
;             bf16_t* dst = seg == 3 ? SZA : SZS;
; #pragma unroll
;             for (int ai = 0; ai < 2; ++ai)
; #pragma unroll
;                 for (int m = 0; m < 4; ++m) {
;                     const int l = lbase + 128 * ai + 16 * m; const int row = b * 2048 + l; const float rsv = rs[row];
; #pragma unroll
;                     for (int bj = 0; bj < 2; ++bj) {
;                         const int col = 256 * half + 64 * wc + 32 * bj + 8 * fq;
;                         const f32x4 v0 = acc[ai][bj][m][0] * rsv, v1 = acc[ai][bj][m][1] * rsv;
;                         *(u32x4*)(dst + (size_t)row * 512 + col) = (u32x4){pk2(siluf_(v0[0]), siluf_(v0[1])), pk2(siluf_(v0[2]), siluf_(v0[3])), pk2(siluf_(v1[0]), siluf_(v1[1])), pk2(siluf_(v1[2]), siluf_(v1[3]))};
;                     }
;                 }
;         }
	v_lshlrev_b64 v[148:149], 10, v[148:149]
	v_lshl_add_u64 v[148:149], s[42:43], 0, v[148:149]
	v_lshl_add_u64 v[156:157], v[148:149], 0, v[146:147]
	v_pk_mul_f32 v[148:149], v[80:81], v[150:151] op_sel_hi:[1,0]
	v_pk_mul_f32 v[152:153], v[78:79], v[150:151] op_sel_hi:[1,0]
	v_pk_mul_f32 v[154:155], v[76:77], v[150:151] op_sel_hi:[1,0]
	v_pk_mul_f32 v[158:159], v[74:75], v[150:151] op_sel_hi:[1,0]
	v_pk_mul_f32 v[160:161], v[72:73], v[150:151] op_sel_hi:[1,0]
	v_pk_mul_f32 v[164:165], v[70:71], v[150:151] op_sel_hi:[1,0]
	v_pk_mul_f32 v[166:167], v[68:69], v[150:151] op_sel_hi:[1,0]
	v_pk_mul_f32 v[168:169], v[66:67], v[150:151] op_sel_hi:[1,0]
	v_mul_f32_e32 v145, 0xbfb8aa3b, v152
	v_mul_f32_e32 v150, 0xbfb8aa3b, v153
	v_mul_f32_e32 v151, 0xbfb8aa3b, v148
	v_mul_f32_e32 v162, 0xbfb8aa3b, v149
	v_mul_f32_e32 v170, 0xbfb8aa3b, v158
	v_mul_f32_e32 v171, 0xbfb8aa3b, v159
	v_mul_f32_e32 v172, 0xbfb8aa3b, v154
	v_mul_f32_e32 v173, 0xbfb8aa3b, v155
	v_mul_f32_e32 v174, 0xbfb8aa3b, v164
	v_mul_f32_e32 v175, 0xbfb8aa3b, v165
	v_exp_f32_e32 v145, v145
	v_exp_f32_e32 v150, v150
	v_exp_f32_e32 v151, v151
	v_exp_f32_e32 v162, v162
	v_exp_f32_e32 v170, v170
	v_exp_f32_e32 v171, v171
	v_exp_f32_e32 v172, v172
	v_exp_f32_e32 v173, v173
	v_exp_f32_e32 v174, v174
	v_exp_f32_e32 v175, v175
	v_mul_f32_e32 v180, 0xbfb8aa3b, v166
	v_mul_f32_e32 v181, 0xbfb8aa3b, v167
	v_exp_f32_e32 v182, v180
	v_exp_f32_e32 v183, v181
	v_add_f32_e32 v145, 1.0, v145
	v_add_f32_e32 v180, 1.0, v150
	v_add_f32_e32 v181, 1.0, v151
	v_add_f32_e32 v162, 1.0, v162
	v_add_f32_e32 v184, 1.0, v170
	v_add_f32_e32 v185, 1.0, v171
	v_add_f32_e32 v204, 1.0, v172
	v_add_f32_e32 v205, 1.0, v173
	v_add_f32_e32 v208, 1.0, v174
	v_add_f32_e32 v209, 1.0, v175
	v_rcp_f32_e32 v150, v145
	v_rcp_f32_e32 v151, v180
	v_rcp_f32_e32 v170, v181
	v_rcp_f32_e32 v171, v162
	v_rcp_f32_e32 v172, v184
	v_rcp_f32_e32 v173, v185
	v_rcp_f32_e32 v174, v204
	v_rcp_f32_e32 v175, v205
	v_mul_f32_e32 v176, 0xbfb8aa3b, v160
	v_mul_f32_e32 v177, 0xbfb8aa3b, v161
	v_mul_f32_e32 v178, 0xbfb8aa3b, v168
	v_mul_f32_e32 v179, 0xbfb8aa3b, v169
	v_exp_f32_e32 v176, v176
	v_exp_f32_e32 v177, v177
	v_exp_f32_e32 v178, v178
	v_exp_f32_e32 v179, v179
	v_pk_mul_f32 v[150:151], v[152:153], v[150:151]
	v_pk_mul_f32 v[152:153], v[148:149], v[170:171]
	v_pk_mul_f32 v[158:159], v[158:159], v[172:173]
	v_pk_mul_f32 v[154:155], v[154:155], v[174:175]
	v_cvt_pk_bf16_f32 v148, v150, v151
	v_cvt_pk_bf16_f32 v149, v152, v153
	v_cvt_pk_bf16_f32 v150, v158, v159
	v_cvt_pk_bf16_f32 v151, v154, v155
	v_add_f32_e32 v145, 1.0, v182
	global_store_dwordx4 v[156:157], v[148:151], off
	v_add_f32_e32 v210, 1.0, v176
	v_add_f32_e32 v211, 1.0, v177
	v_rcp_f32_e32 v148, v145
	v_add_f32_e32 v145, 1.0, v183
	v_add_f32_e32 v214, 1.0, v178
	v_add_f32_e32 v215, 1.0, v179
	v_rcp_f32_e32 v149, v145
	v_rcp_f32_e32 v176, v208
	v_rcp_f32_e32 v177, v209
	v_rcp_f32_e32 v178, v210
	v_rcp_f32_e32 v179, v211
	v_rcp_f32_e32 v180, v214
	v_rcp_f32_e32 v181, v215
	v_pk_mul_f32 v[148:149], v[166:167], v[148:149]
	v_pk_mul_f32 v[164:165], v[164:165], v[176:177]
	v_pk_mul_f32 v[160:161], v[160:161], v[178:179]
	v_pk_mul_f32 v[150:151], v[168:169], v[180:181]
	v_cvt_pk_bf16_f32 v155, v148, v149
	v_add_u32_e32 v148, 0x80, v144
	v_cvt_pk_bf16_f32 v152, v164, v165
	v_cvt_pk_bf16_f32 v153, v160, v161
	v_cvt_pk_bf16_f32 v154, v150, v151
	v_ashrrev_i32_e32 v149, 31, v148
	global_store_dwordx4 v[156:157], v[152:155], off offset:64
	v_lshl_add_u64 v[150:151], v[148:149], 2, s[20:21]
	v_mov_b32_e32 v150, v222
	v_lshlrev_b64 v[148:149], 10, v[148:149]
	v_lshl_add_u64 v[148:149], s[42:43], 0, v[148:149]
	v_lshl_add_u64 v[156:157], v[148:149], 0, v[146:147]
	v_pk_mul_f32 v[148:149], v[64:65], v[150:151] op_sel_hi:[1,0]
	v_pk_mul_f32 v[152:153], v[62:63], v[150:151] op_sel_hi:[1,0]
	v_pk_mul_f32 v[154:155], v[60:61], v[150:151] op_sel_hi:[1,0]
	v_pk_mul_f32 v[158:159], v[58:59], v[150:151] op_sel_hi:[1,0]
	v_pk_mul_f32 v[160:161], v[56:57], v[150:151] op_sel_hi:[1,0]
	v_pk_mul_f32 v[164:165], v[54:55], v[150:151] op_sel_hi:[1,0]
	v_pk_mul_f32 v[166:167], v[52:53], v[150:151] op_sel_hi:[1,0]
	v_pk_mul_f32 v[168:169], v[50:51], v[150:151] op_sel_hi:[1,0]
	v_mul_f32_e32 v145, 0xbfb8aa3b, v152
	v_mul_f32_e32 v150, 0xbfb8aa3b, v153
	v_mul_f32_e32 v151, 0xbfb8aa3b, v148
	v_mul_f32_e32 v162, 0xbfb8aa3b, v149
	v_mul_f32_e32 v170, 0xbfb8aa3b, v158
	v_mul_f32_e32 v171, 0xbfb8aa3b, v159
	v_mul_f32_e32 v172, 0xbfb8aa3b, v154
	v_mul_f32_e32 v173, 0xbfb8aa3b, v155
	v_mul_f32_e32 v174, 0xbfb8aa3b, v164
	v_mul_f32_e32 v175, 0xbfb8aa3b, v165
	v_exp_f32_e32 v145, v145
	v_exp_f32_e32 v150, v150
	v_exp_f32_e32 v151, v151
	v_exp_f32_e32 v162, v162
	v_exp_f32_e32 v170, v170
	v_exp_f32_e32 v171, v171
	v_exp_f32_e32 v172, v172
	v_exp_f32_e32 v173, v173
	v_exp_f32_e32 v174, v174
	v_exp_f32_e32 v175, v175
	v_add_f32_e32 v145, 1.0, v145
	v_add_f32_e32 v180, 1.0, v150
	v_add_f32_e32 v182, 1.0, v151
	v_add_f32_e32 v162, 1.0, v162
	v_add_f32_e32 v183, 1.0, v170
	v_add_f32_e32 v184, 1.0, v171
	v_add_f32_e32 v185, 1.0, v172
	v_add_f32_e32 v204, 1.0, v173
	v_add_f32_e32 v205, 1.0, v174
	v_add_f32_e32 v208, 1.0, v175
	v_rcp_f32_e32 v150, v145
	v_rcp_f32_e32 v151, v180
	v_rcp_f32_e32 v170, v182
	v_rcp_f32_e32 v171, v162
	v_rcp_f32_e32 v172, v183
	v_rcp_f32_e32 v173, v184
	v_rcp_f32_e32 v174, v185
	v_rcp_f32_e32 v175, v204
	v_pk_mul_f32 v[150:151], v[152:153], v[150:151]
	v_pk_mul_f32 v[152:153], v[148:149], v[170:171]
	v_pk_mul_f32 v[158:159], v[158:159], v[172:173]
	v_pk_mul_f32 v[154:155], v[154:155], v[174:175]
	v_mul_f32_e32 v181, 0xbfb8aa3b, v166
	v_cvt_pk_bf16_f32 v148, v150, v151
	v_cvt_pk_bf16_f32 v149, v152, v153
; __device__ __forceinline__ unsigned pk2(float lo, float hi) { const f32x2c_t v = {lo, hi}; return __builtin_bit_cast(unsigned, __builtin_convertvector(v, bf16x2c_t)); }
; __device__ __forceinline__ float siluf_(float v) { return v * sigmoidf_(v); }
;     __device__ __forceinline__ void operator()(const f32x4 (&acc)[2][2][4][2], const Unit& u, int wr, int wc, int fr, int fq) const {
;     ...
;         } else {
;             bf16_t* dst = seg == 3 ? SZA : SZS;
; #pragma unroll
;             for (int ai = 0; ai < 2; ++ai)
; #pragma unroll
;                 for (int m = 0; m < 4; ++m) {
;                     const int l = lbase + 128 * ai + 16 * m; const int row = b * 2048 + l; const float rsv = rs[row];
; #pragma unroll
;                     for (int bj = 0; bj < 2; ++bj) {
;                         const int col = 256 * half + 64 * wc + 32 * bj + 8 * fq;
;                         const f32x4 v0 = acc[ai][bj][m][0] * rsv, v1 = acc[ai][bj][m][1] * rsv;
;                         *(u32x4*)(dst + (size_t)row * 512 + col) = (u32x4){pk2(siluf_(v0[0]), siluf_(v0[1])), pk2(siluf_(v0[2]), siluf_(v0[3])), pk2(siluf_(v1[0]), siluf_(v1[1])), pk2(siluf_(v1[2]), siluf_(v1[3]))};
;                     }
;                 }
;         }
	v_cvt_pk_bf16_f32 v150, v158, v159
	v_cvt_pk_bf16_f32 v151, v154, v155
	global_store_dwordx4 v[156:157], v[148:151], off
	v_exp_f32_e32 v145, v181
	v_mul_f32_e32 v176, 0xbfb8aa3b, v160
	v_mul_f32_e32 v148, 0xbfb8aa3b, v167
	v_mul_f32_e32 v177, 0xbfb8aa3b, v161
	v_mul_f32_e32 v178, 0xbfb8aa3b, v168
	v_mul_f32_e32 v179, 0xbfb8aa3b, v169
	v_exp_f32_e32 v149, v148
	v_exp_f32_e32 v176, v176
	v_exp_f32_e32 v177, v177
	v_exp_f32_e32 v178, v178
	v_exp_f32_e32 v179, v179
	v_add_f32_e32 v145, 1.0, v145
	v_rcp_f32_e32 v148, v145
	v_add_f32_e32 v145, 1.0, v149
	v_add_f32_e32 v209, 1.0, v176
	v_add_f32_e32 v210, 1.0, v177
	v_add_f32_e32 v211, 1.0, v178
	v_add_f32_e32 v214, 1.0, v179
	v_rcp_f32_e32 v149, v145
	v_rcp_f32_e32 v176, v205
	v_rcp_f32_e32 v177, v208
	v_rcp_f32_e32 v178, v209
	v_rcp_f32_e32 v179, v210
	v_rcp_f32_e32 v180, v211
	v_rcp_f32_e32 v181, v214
	v_pk_mul_f32 v[148:149], v[166:167], v[148:149]
	v_pk_mul_f32 v[164:165], v[164:165], v[176:177]
	v_pk_mul_f32 v[160:161], v[160:161], v[178:179]
	v_pk_mul_f32 v[150:151], v[168:169], v[180:181]
	v_cvt_pk_bf16_f32 v155, v148, v149
	v_add_u32_e32 v148, 0x90, v144
	v_cvt_pk_bf16_f32 v152, v164, v165
	v_cvt_pk_bf16_f32 v153, v160, v161
	v_cvt_pk_bf16_f32 v154, v150, v151
	v_ashrrev_i32_e32 v149, 31, v148
	global_store_dwordx4 v[156:157], v[152:155], off offset:64
	v_lshl_add_u64 v[150:151], v[148:149], 2, s[20:21]
	v_mov_b32_e32 v150, v223
	v_lshlrev_b64 v[148:149], 10, v[148:149]
	v_lshl_add_u64 v[148:149], s[42:43], 0, v[148:149]
	v_lshl_add_u64 v[156:157], v[148:149], 0, v[146:147]
	v_pk_mul_f32 v[148:149], v[48:49], v[150:151] op_sel_hi:[1,0]
	v_pk_mul_f32 v[152:153], v[46:47], v[150:151] op_sel_hi:[1,0]
	v_pk_mul_f32 v[154:155], v[44:45], v[150:151] op_sel_hi:[1,0]
	v_pk_mul_f32 v[158:159], v[42:43], v[150:151] op_sel_hi:[1,0]
	v_pk_mul_f32 v[160:161], v[40:41], v[150:151] op_sel_hi:[1,0]
	v_pk_mul_f32 v[164:165], v[38:39], v[150:151] op_sel_hi:[1,0]
	v_pk_mul_f32 v[166:167], v[36:37], v[150:151] op_sel_hi:[1,0]
	v_pk_mul_f32 v[168:169], v[34:35], v[150:151] op_sel_hi:[1,0]
	v_mul_f32_e32 v145, 0xbfb8aa3b, v152
	v_mul_f32_e32 v150, 0xbfb8aa3b, v153
	v_mul_f32_e32 v151, 0xbfb8aa3b, v148
	v_mul_f32_e32 v162, 0xbfb8aa3b, v149
	v_mul_f32_e32 v170, 0xbfb8aa3b, v158
	v_mul_f32_e32 v171, 0xbfb8aa3b, v159
	v_mul_f32_e32 v172, 0xbfb8aa3b, v154
	v_mul_f32_e32 v173, 0xbfb8aa3b, v155
	v_mul_f32_e32 v174, 0xbfb8aa3b, v164
	v_mul_f32_e32 v175, 0xbfb8aa3b, v165
	v_exp_f32_e32 v145, v145
	v_exp_f32_e32 v150, v150
	v_exp_f32_e32 v151, v151
	v_exp_f32_e32 v162, v162
	v_exp_f32_e32 v170, v170
	v_exp_f32_e32 v171, v171
	v_exp_f32_e32 v172, v172
	v_exp_f32_e32 v173, v173
	v_exp_f32_e32 v174, v174
	v_exp_f32_e32 v175, v175
	v_mul_f32_e32 v179, 0xbfb8aa3b, v169
	v_exp_f32_e32 v180, v179
	v_add_f32_e32 v145, 1.0, v145
	v_add_f32_e32 v179, 1.0, v150
	v_add_f32_e32 v181, 1.0, v151
	v_add_f32_e32 v162, 1.0, v162
	v_add_f32_e32 v182, 1.0, v170
	v_add_f32_e32 v183, 1.0, v171
	v_add_f32_e32 v184, 1.0, v172
	v_add_f32_e32 v185, 1.0, v173
	v_add_f32_e32 v204, 1.0, v174
	v_add_f32_e32 v205, 1.0, v175
	v_rcp_f32_e32 v150, v145
	v_rcp_f32_e32 v151, v179
	v_rcp_f32_e32 v170, v181
	v_rcp_f32_e32 v171, v162
	v_rcp_f32_e32 v172, v182
	v_rcp_f32_e32 v173, v183
	v_rcp_f32_e32 v174, v184
	v_rcp_f32_e32 v175, v185
	v_pk_mul_f32 v[150:151], v[152:153], v[150:151]
	v_pk_mul_f32 v[152:153], v[148:149], v[170:171]
	v_pk_mul_f32 v[158:159], v[158:159], v[172:173]
	v_pk_mul_f32 v[154:155], v[154:155], v[174:175]
	v_cvt_pk_bf16_f32 v148, v150, v151
	v_cvt_pk_bf16_f32 v149, v152, v153
	v_cvt_pk_bf16_f32 v150, v158, v159
	v_cvt_pk_bf16_f32 v151, v154, v155
	v_mul_f32_e32 v178, 0xbfb8aa3b, v168
	global_store_dwordx4 v[156:157], v[148:151], off
	v_exp_f32_e32 v178, v178
	v_mul_f32_e32 v176, 0xbfb8aa3b, v160
	v_mul_f32_e32 v149, 0xbfb8aa3b, v166
	v_exp_f32_e32 v150, v149
	v_mul_f32_e32 v149, 0xbfb8aa3b, v167
	v_mul_f32_e32 v177, 0xbfb8aa3b, v161
	v_exp_f32_e32 v151, v149
	v_exp_f32_e32 v176, v176
	v_exp_f32_e32 v177, v177
	v_add_f32_e32 v145, 1.0, v180
	v_add_f32_e32 v210, 1.0, v178
	v_rcp_f32_e32 v149, v145
	v_add_f32_e32 v145, 1.0, v150
	v_rcp_f32_e32 v148, v210
	v_rcp_f32_e32 v150, v145
	v_add_f32_e32 v145, 1.0, v151
	v_add_f32_e32 v208, 1.0, v176
	v_add_f32_e32 v209, 1.0, v177
	v_rcp_f32_e32 v151, v145
	v_rcp_f32_e32 v176, v204
	v_rcp_f32_e32 v177, v205
	v_rcp_f32_e32 v178, v208
	v_rcp_f32_e32 v179, v209
	v_pk_mul_f32 v[148:149], v[168:169], v[148:149]
	v_pk_mul_f32 v[164:165], v[164:165], v[176:177]
	v_cvt_pk_bf16_f32 v154, v148, v149
	v_pk_mul_f32 v[148:149], v[166:167], v[150:151]
	v_pk_mul_f32 v[160:161], v[160:161], v[178:179]
	v_cvt_pk_bf16_f32 v155, v148, v149
	v_add_u32_e32 v148, 0xa0, v144
	v_cvt_pk_bf16_f32 v152, v164, v165
	v_cvt_pk_bf16_f32 v153, v160, v161
	v_ashrrev_i32_e32 v149, 31, v148
	global_store_dwordx4 v[156:157], v[152:155], off offset:64
	v_lshl_add_u64 v[150:151], v[148:149], 2, s[20:21]
	v_mov_b32_e32 v150, v224
	v_lshlrev_b64 v[148:149], 10, v[148:149]
	v_lshl_add_u64 v[148:149], s[42:43], 0, v[148:149]
	v_lshl_add_u64 v[156:157], v[148:149], 0, v[146:147]
	v_add_u32_e32 v144, 0xb0, v144
	v_pk_mul_f32 v[148:149], v[32:33], v[150:151] op_sel_hi:[1,0]
	v_pk_mul_f32 v[152:153], v[30:31], v[150:151] op_sel_hi:[1,0]
	v_pk_mul_f32 v[154:155], v[28:29], v[150:151] op_sel_hi:[1,0]
	v_pk_mul_f32 v[158:159], v[26:27], v[150:151] op_sel_hi:[1,0]
	v_pk_mul_f32 v[160:161], v[24:25], v[150:151] op_sel_hi:[1,0]
	v_pk_mul_f32 v[164:165], v[22:23], v[150:151] op_sel_hi:[1,0]
	v_pk_mul_f32 v[166:167], v[20:21], v[150:151] op_sel_hi:[1,0]
	v_pk_mul_f32 v[168:169], v[18:19], v[150:151] op_sel_hi:[1,0]
	v_mul_f32_e32 v145, 0xbfb8aa3b, v152
; __device__ __forceinline__ unsigned pk2(float lo, float hi) { const f32x2c_t v = {lo, hi}; return __builtin_bit_cast(unsigned, __builtin_convertvector(v, bf16x2c_t)); }
; __device__ __forceinline__ float siluf_(float v) { return v * sigmoidf_(v); }
;     __device__ __forceinline__ void operator()(const f32x4 (&acc)[2][2][4][2], const Unit& u, int wr, int wc, int fr, int fq) const {
;     ...
;         } else {
;             bf16_t* dst = seg == 3 ? SZA : SZS;
; #pragma unroll
;             for (int ai = 0; ai < 2; ++ai)
; #pragma unroll
;                 for (int m = 0; m < 4; ++m) {
;                     const int l = lbase + 128 * ai + 16 * m; const int row = b * 2048 + l; const float rsv = rs[row];
; #pragma unroll
;                     for (int bj = 0; bj < 2; ++bj) {
;                         const int col = 256 * half + 64 * wc + 32 * bj + 8 * fq;
;                         const f32x4 v0 = acc[ai][bj][m][0] * rsv, v1 = acc[ai][bj][m][1] * rsv;
;                         *(u32x4*)(dst + (size_t)row * 512 + col) = (u32x4){pk2(siluf_(v0[0]), siluf_(v0[1])), pk2(siluf_(v0[2]), siluf_(v0[3])), pk2(siluf_(v1[0]), siluf_(v1[1])), pk2(siluf_(v1[2]), siluf_(v1[3]))};
;                     }
;                 }
;         }
	v_mul_f32_e32 v150, 0xbfb8aa3b, v153
	v_mul_f32_e32 v151, 0xbfb8aa3b, v148
	v_mul_f32_e32 v162, 0xbfb8aa3b, v149
	v_mul_f32_e32 v170, 0xbfb8aa3b, v158
	v_mul_f32_e32 v171, 0xbfb8aa3b, v159
	v_mul_f32_e32 v172, 0xbfb8aa3b, v154
	v_mul_f32_e32 v173, 0xbfb8aa3b, v155
	v_mul_f32_e32 v174, 0xbfb8aa3b, v164
	v_mul_f32_e32 v175, 0xbfb8aa3b, v165
	v_exp_f32_e32 v145, v145
	v_exp_f32_e32 v150, v150
	v_exp_f32_e32 v151, v151
	v_exp_f32_e32 v162, v162
	v_exp_f32_e32 v170, v170
	v_exp_f32_e32 v171, v171
	v_exp_f32_e32 v172, v172
	v_exp_f32_e32 v173, v173
	v_exp_f32_e32 v174, v174
	v_exp_f32_e32 v175, v175
	v_mul_f32_e32 v178, 0xbfb8aa3b, v168
	v_exp_f32_e32 v181, v178
	v_add_f32_e32 v145, 1.0, v145
	v_add_f32_e32 v178, 1.0, v150
	v_add_f32_e32 v179, 1.0, v151
	v_add_f32_e32 v162, 1.0, v162
	v_add_f32_e32 v182, 1.0, v170
	v_add_f32_e32 v183, 1.0, v171
	v_add_f32_e32 v184, 1.0, v172
	v_add_f32_e32 v185, 1.0, v173
	v_add_f32_e32 v204, 1.0, v174
	v_add_f32_e32 v205, 1.0, v175
	v_rcp_f32_e32 v150, v145
	v_rcp_f32_e32 v151, v178
	v_rcp_f32_e32 v170, v179
	v_rcp_f32_e32 v171, v162
	v_rcp_f32_e32 v172, v182
	v_rcp_f32_e32 v173, v183
	v_rcp_f32_e32 v174, v184
	v_rcp_f32_e32 v175, v185
	v_pk_mul_f32 v[150:151], v[152:153], v[150:151]
	v_pk_mul_f32 v[152:153], v[148:149], v[170:171]
	v_pk_mul_f32 v[158:159], v[158:159], v[172:173]
	v_pk_mul_f32 v[154:155], v[154:155], v[174:175]
	v_mul_f32_e32 v176, 0xbfb8aa3b, v160
	v_mul_f32_e32 v177, 0xbfb8aa3b, v161
	v_mul_f32_e32 v180, 0xbfb8aa3b, v169
	v_cvt_pk_bf16_f32 v148, v150, v151
	v_cvt_pk_bf16_f32 v149, v152, v153
	v_cvt_pk_bf16_f32 v150, v158, v159
	v_cvt_pk_bf16_f32 v151, v154, v155
	v_exp_f32_e32 v176, v176
	v_exp_f32_e32 v177, v177
	global_store_dwordx4 v[156:157], v[148:151], off
	v_exp_f32_e32 v145, v180
	v_add_f32_e32 v208, 1.0, v176
	v_mul_f32_e32 v151, 0xbfb8aa3b, v166
	v_exp_f32_e32 v153, v151
	v_mul_f32_e32 v151, 0xbfb8aa3b, v167
	v_exp_f32_e32 v154, v151
	v_add_f32_e32 v209, 1.0, v177
	v_add_f32_e32 v145, 1.0, v145
	v_rcp_f32_e32 v178, v208
	v_rcp_f32_e32 v179, v209
	v_add_f32_e32 v150, 1.0, v181
	v_rcp_f32_e32 v151, v145
	v_add_f32_e32 v145, 1.0, v153
	v_rcp_f32_e32 v150, v150
	v_rcp_f32_e32 v158, v145
	v_add_f32_e32 v145, 1.0, v154
	v_rcp_f32_e32 v176, v204
	v_rcp_f32_e32 v177, v205
	v_rcp_f32_e32 v159, v145
	v_pk_mul_f32 v[148:149], v[160:161], v[178:179]
	v_ashrrev_i32_e32 v145, 31, v144
	v_cvt_pk_bf16_f32 v153, v148, v149
	v_pk_mul_f32 v[148:149], v[168:169], v[150:151]
	v_pk_mul_f32 v[164:165], v[164:165], v[176:177]
	v_cvt_pk_bf16_f32 v154, v148, v149
	v_pk_mul_f32 v[148:149], v[166:167], v[158:159]
	v_cvt_pk_bf16_f32 v152, v164, v165
	v_cvt_pk_bf16_f32 v155, v148, v149
	global_store_dwordx4 v[156:157], v[152:155], off offset:64
	v_lshl_add_u64 v[148:149], v[144:145], 2, s[20:21]
	v_mov_b32_e32 v148, v225
	v_lshlrev_b64 v[144:145], 10, v[144:145]
	v_lshl_add_u64 v[144:145], s[42:43], 0, v[144:145]
	v_lshl_add_u64 v[152:153], v[144:145], 0, v[146:147]
	v_pk_mul_f32 v[144:145], v[16:17], v[148:149] op_sel_hi:[1,0]
	v_pk_mul_f32 v[146:147], v[14:15], v[148:149] op_sel_hi:[1,0]
	v_pk_mul_f32 v[150:151], v[12:13], v[148:149] op_sel_hi:[1,0]
	v_pk_mul_f32 v[154:155], v[10:11], v[148:149] op_sel_hi:[1,0]
	v_pk_mul_f32 v[156:157], v[8:9], v[148:149] op_sel_hi:[1,0]
	v_pk_mul_f32 v[158:159], v[6:7], v[148:149] op_sel_hi:[1,0]
	v_pk_mul_f32 v[160:161], v[4:5], v[148:149] op_sel_hi:[1,0]
	v_pk_mul_f32 v[164:165], v[2:3], v[148:149] op_sel_hi:[1,0]
	v_mul_f32_e32 v148, 0xbfb8aa3b, v146
	v_mul_f32_e32 v149, 0xbfb8aa3b, v147
	v_mul_f32_e32 v162, 0xbfb8aa3b, v144
	v_mul_f32_e32 v166, 0xbfb8aa3b, v145
	v_mul_f32_e32 v167, 0xbfb8aa3b, v154
	v_mul_f32_e32 v168, 0xbfb8aa3b, v155
	v_mul_f32_e32 v169, 0xbfb8aa3b, v150
	v_mul_f32_e32 v170, 0xbfb8aa3b, v151
	v_mul_f32_e32 v171, 0xbfb8aa3b, v158
	v_exp_f32_e32 v148, v148
	v_exp_f32_e32 v149, v149
	v_exp_f32_e32 v162, v162
	v_exp_f32_e32 v166, v166
	v_exp_f32_e32 v167, v167
	v_exp_f32_e32 v168, v168
	v_exp_f32_e32 v169, v169
	v_exp_f32_e32 v170, v170
	v_exp_f32_e32 v171, v171
	v_add_f32_e32 v148, 1.0, v148
	v_add_f32_e32 v149, 1.0, v149
	v_add_f32_e32 v162, 1.0, v162
	v_add_f32_e32 v175, 1.0, v166
	v_add_f32_e32 v176, 1.0, v167
	v_add_f32_e32 v177, 1.0, v168
	v_add_f32_e32 v178, 1.0, v169
	v_add_f32_e32 v179, 1.0, v170
	v_add_f32_e32 v180, 1.0, v171
	v_rcp_f32_e32 v148, v148
	v_rcp_f32_e32 v149, v149
	v_rcp_f32_e32 v166, v162
	v_rcp_f32_e32 v167, v175
	v_rcp_f32_e32 v168, v176
	v_rcp_f32_e32 v169, v177
	v_rcp_f32_e32 v170, v178
	v_rcp_f32_e32 v171, v179
	v_pk_mul_f32 v[146:147], v[146:147], v[148:149]
	v_pk_mul_f32 v[148:149], v[144:145], v[166:167]
	v_pk_mul_f32 v[154:155], v[154:155], v[168:169]
	v_pk_mul_f32 v[150:151], v[150:151], v[170:171]
	v_cvt_pk_bf16_f32 v144, v146, v147
	v_cvt_pk_bf16_f32 v145, v148, v149
	v_cvt_pk_bf16_f32 v146, v154, v155
	v_cvt_pk_bf16_f32 v147, v150, v151
	v_mul_f32_e32 v173, 0xbfb8aa3b, v156
	v_mul_f32_e32 v174, 0xbfb8aa3b, v157
	global_store_dwordx4 v[152:153], v[144:147], off
	v_exp_f32_e32 v173, v173
	v_exp_f32_e32 v174, v174
	v_mul_f32_e32 v144, 0xbfb8aa3b, v164
	v_exp_f32_e32 v146, v144
	v_mul_f32_e32 v144, 0xbfb8aa3b, v165
	v_mul_f32_e32 v149, 0xbfb8aa3b, v160
	v_mul_f32_e32 v172, 0xbfb8aa3b, v159
	v_exp_f32_e32 v147, v144
	v_exp_f32_e32 v149, v149
	v_mul_f32_e32 v150, 0xbfb8aa3b, v161
	v_exp_f32_e32 v172, v172
	v_exp_f32_e32 v150, v150
	v_add_f32_e32 v182, 1.0, v173
	v_add_f32_e32 v183, 1.0, v174
	v_rcp_f32_e32 v174, v182
	v_rcp_f32_e32 v175, v183
	v_add_f32_e32 v146, 1.0, v146
	v_add_f32_e32 v147, 1.0, v147
	v_add_f32_e32 v149, 1.0, v149
	v_add_f32_e32 v181, 1.0, v172
	v_rcp_f32_e32 v146, v146
	v_rcp_f32_e32 v147, v147
	v_rcp_f32_e32 v154, v149
	v_add_f32_e32 v149, 1.0, v150
	v_rcp_f32_e32 v172, v180
	v_rcp_f32_e32 v173, v181
	v_rcp_f32_e32 v155, v149
	v_pk_mul_f32 v[144:145], v[156:157], v[174:175]
	v_pk_mul_f32 v[158:159], v[158:159], v[172:173]
	v_cvt_pk_bf16_f32 v149, v144, v145
	v_pk_mul_f32 v[144:145], v[164:165], v[146:147]
	v_cvt_pk_bf16_f32 v148, v158, v159
	v_cvt_pk_bf16_f32 v150, v144, v145
	v_pk_mul_f32 v[144:145], v[160:161], v[154:155]
	s_nop 0
	v_cvt_pk_bf16_f32 v151, v144, v145
	global_store_dwordx4 v[152:153], v[148:151], off offset:64

; __device__ __forceinline__ unsigned pk2(float lo, float hi) { const f32x2c_t v = {lo, hi}; return __builtin_bit_cast(unsigned, __builtin_convertvector(v, bf16x2c_t)); }
;     __device__ __forceinline__ void operator()(const f32x4 (&acc)[2][2][4][2], const Unit& u, int wr, int wc, int fr, int fq) const {
;     ...
;         if (seg <= 1) {
;             bf16_t* dst = seg == 0 ? Q : Kk; const float qs = seg == 0 ? 0.18033688011112042f : 1.0f;
;             const int head = 4 * half + wc;
;             f32x4 cl[2], ch[2];
; #pragma unroll
;             for (int n = 0; n < 2; ++n) { cl[n] = (f32x4){0.f, 0.f, 0.f, 0.f}; ch[n] = (f32x4){0.f, 0.f, 0.f, 0.f}; }
;             bf16_t* obase = dst + ((size_t)((b * 8 + head) * 2048)) * 64 + 8 * fq;
; #pragma unroll
;             for (int ai = 0; ai < 2; ++ai)
; #pragma unroll
;                 for (int m = 0; m < 4; ++m) {
;                     const int l = lbase + 128 * ai + 16 * m; const float rsv = rs[b * 2048 + l] * qs;
;                     unsigned wl[4], wh[4];
; #pragma unroll
;                     for (int n = 0; n < 2; ++n) {
;                         const f32x4 c4 = *(const f32x4*)(cosT + l * 32 + 8 * fq + 4 * n), s4 = *(const f32x4*)(sinT + l * 32 + 8 * fq + 4 * n);
;                         const f32x4 t1 = acc[ai][0][m][n] * rsv, t2 = acc[ai][1][m][n] * rsv;
;                         const f32x4 lo = t1 * c4 - t2 * s4, hi = t2 * c4 + t1 * s4;
;                         wl[2 * n] = pk2(lo[0], lo[1]); wl[2 * n + 1] = pk2(lo[2], lo[3]); wh[2 * n] = pk2(hi[0], hi[1]); wh[2 * n + 1] = pk2(hi[2], hi[3]);
;                         cl[n] += lo; ch[n] += hi;
;                     }
;                     bf16_t* o = obase + (unsigned)l * 64u;
;                     *(u32x4*)o = (u32x4){wl[0], wl[1], wl[2], wl[3]};
;                     *(u32x4*)(o + 32) = (u32x4){wh[0], wh[1], wh[2], wh[3]};
;                 }
.LBB0_206:
	s_and_b64 vcc, exec, s[42:43]
	s_cbranch_vccz .LBB0_225
	s_cmp_lt_u32 s40, 2
	s_cselect_b64 vcc, -1, 0
	s_and_b64 s[42:43], vcc, exec
	s_cselect_b32 s40, s13, s7
	s_cselect_b32 s44, s12, s6
	s_lshl_b32 s42, s46, 2
	s_and_b32 s38, s38, -8
	s_or_b32 s38, s42, s38
	s_or_b32 s38, s38, s51
	s_lshl_b32 s42, s38, 11
	s_ashr_i32 s43, s42, 31
	s_lshl_b64 s[42:43], s[42:43], 7
	s_add_u32 s42, s44, s42
	s_addc_u32 s43, s40, s43
	s_lshl_b32 s39, s39, 11
	v_add_u32_e32 v144, s39, v203
	v_ashrrev_i32_e32 v145, 31, v144
	v_lshl_add_u64 v[144:145], v[144:145], 2, s[20:21]
	global_load_dword v147, v[144:145], off
	v_lshlrev_b32_e32 v144, 5, v203
	v_mov_b32_e32 v145, v131
	v_lshlrev_b64 v[144:145], 2, v[144:145]
	v_lshl_add_u64 v[156:157], v[134:135], 0, v[144:145]
	global_load_dwordx4 v[148:151], v[156:157], off
	v_lshl_add_u64 v[144:145], v[132:133], 0, v[144:145]
	global_load_dwordx4 v[152:155], v[144:145], off
	s_nop 0
	global_load_dwordx4 v[156:159], v[156:157], off offset:16
	s_nop 0
	global_load_dwordx4 v[164:167], v[144:145], off offset:16
	v_cndmask_b32_e32 v146, 1.0, v193, vcc
	v_or_b32_e32 v184, 16, v203
	v_lshlrev_b32_e32 v160, 6, v203
	v_mov_b32_e32 v161, v131
	v_lshl_add_u64 v[144:145], s[42:43], 0, v[130:131]
	v_add_u32_e32 v168, s39, v184
	v_lshl_add_u64 v[160:161], v[160:161], 1, v[144:145]
	v_ashrrev_i32_e32 v169, 31, v168
	v_lshl_add_u64 v[168:169], v[168:169], 2, s[20:21]
	s_cmp_lg_u32 s29, 1
	s_waitcnt vmcnt(0)
	v_mul_f32_e32 v162, v146, v147
	v_pk_mul_f32 v[118:119], v[118:119], v[162:163] op_sel_hi:[1,0]
	v_pk_mul_f32 v[120:121], v[120:121], v[162:163] op_sel_hi:[1,0]
	v_pk_mul_f32 v[114:115], v[114:115], v[162:163] op_sel_hi:[1,0]
	v_pk_mul_f32 v[116:117], v[116:117], v[162:163] op_sel_hi:[1,0]
	v_pk_mul_f32 v[170:171], v[126:127], v[162:163] op_sel_hi:[1,0]
	v_pk_mul_f32 v[128:129], v[128:129], v[162:163] op_sel_hi:[1,0]
	v_pk_mul_f32 v[172:173], v[122:123], v[162:163] op_sel_hi:[1,0]
	v_pk_mul_f32 v[174:175], v[124:125], v[162:163] op_sel_hi:[1,0]
	v_pk_mul_f32 v[122:123], v[150:151], v[120:121]
	v_pk_mul_f32 v[126:127], v[148:149], v[118:119]
	v_pk_mul_f32 v[120:121], v[154:155], v[120:121]
	v_pk_mul_f32 v[118:119], v[152:153], v[118:119]
	v_pk_mul_f32 v[176:177], v[158:159], v[116:117]
	v_pk_mul_f32 v[178:179], v[156:157], v[114:115]
	v_pk_mul_f32 v[180:181], v[166:167], v[116:117]
	v_pk_mul_f32 v[182:183], v[164:165], v[114:115]
	v_pk_fma_f32 v[124:125], v[154:155], v[128:129], v[122:123] neg_lo:[0,0,1] neg_hi:[0,0,1]
	v_pk_fma_f32 v[126:127], v[152:153], v[170:171], v[126:127] neg_lo:[0,0,1] neg_hi:[0,0,1]
	v_pk_fma_f32 v[122:123], v[150:151], v[128:129], v[120:121]
	v_pk_fma_f32 v[128:129], v[148:149], v[170:171], v[118:119]
	v_pk_fma_f32 v[116:117], v[166:167], v[174:175], v[176:177] neg_lo:[0,0,1] neg_hi:[0,0,1]
	v_pk_fma_f32 v[118:119], v[164:165], v[172:173], v[178:179] neg_lo:[0,0,1] neg_hi:[0,0,1]
	v_pk_fma_f32 v[114:115], v[158:159], v[174:175], v[180:181]
	v_pk_fma_f32 v[120:121], v[156:157], v[172:173], v[182:183]
	v_cvt_pk_bf16_f32 v218, v126, v127
	v_cvt_pk_bf16_f32 v219, v124, v125
	v_cvt_pk_bf16_f32 v220, v118, v119
	v_cvt_pk_bf16_f32 v221, v116, v117
	v_cvt_pk_bf16_f32 v222, v128, v129
	v_cvt_pk_bf16_f32 v223, v122, v123
	v_cvt_pk_bf16_f32 v224, v120, v121
	v_cvt_pk_bf16_f32 v225, v114, v115
	v_mov_b64_e32 v[234:235], v[160:161]
	global_load_dword v147, v[168:169], off
	v_mov_b32_e32 v149, v131
	v_lshlrev_b32_e32 v148, 5, v184
	v_lshlrev_b64 v[152:153], 2, v[148:149]
	v_lshl_add_u64 v[156:157], v[134:135], 0, v[152:153]
	global_load_dwordx4 v[148:151], v[156:157], off
	v_lshl_add_u64 v[160:161], v[132:133], 0, v[152:153]
	global_load_dwordx4 v[152:155], v[160:161], off
	s_nop 0
	global_load_dwordx4 v[156:159], v[156:157], off offset:16
	s_nop 0
	global_load_dwordx4 v[164:167], v[160:161], off offset:16
	global_store_dwordx4 v[234:235], v[218:221], off
	global_store_dwordx4 v[234:235], v[222:225], off offset:64
	v_or_b32_e32 v182, 32, v203
	v_mov_b32_e32 v161, v131
	v_lshlrev_b32_e32 v160, 6, v184
	v_add_u32_e32 v168, s39, v182
	v_lshl_add_u64 v[160:161], v[160:161], 1, v[144:145]
	v_ashrrev_i32_e32 v169, 31, v168
	v_lshl_add_u64 v[168:169], v[168:169], 2, s[20:21]
	v_or_b32_e32 v183, 48, v203
	s_waitcnt vmcnt(6)
	v_mul_f32_e32 v162, v146, v147
	v_pk_mul_f32 v[104:105], v[104:105], v[162:163] op_sel_hi:[1,0]
	v_pk_mul_f32 v[102:103], v[102:103], v[162:163] op_sel_hi:[1,0]
	v_pk_mul_f32 v[100:101], v[100:101], v[162:163] op_sel_hi:[1,0]
	v_pk_mul_f32 v[98:99], v[98:99], v[162:163] op_sel_hi:[1,0]
	v_pk_mul_f32 v[170:171], v[110:111], v[162:163] op_sel_hi:[1,0]
	v_pk_mul_f32 v[112:113], v[112:113], v[162:163] op_sel_hi:[1,0]
	v_pk_mul_f32 v[172:173], v[106:107], v[162:163] op_sel_hi:[1,0]
	v_pk_mul_f32 v[174:175], v[108:109], v[162:163] op_sel_hi:[1,0]
	s_waitcnt vmcnt(5)
	v_pk_mul_f32 v[106:107], v[148:149], v[102:103]
	v_pk_mul_f32 v[108:109], v[150:151], v[104:105]
	s_waitcnt vmcnt(4)
	v_pk_mul_f32 v[102:103], v[152:153], v[102:103]
	v_pk_mul_f32 v[104:105], v[154:155], v[104:105]
	s_waitcnt vmcnt(3)
	v_pk_mul_f32 v[176:177], v[156:157], v[98:99]
	v_pk_mul_f32 v[178:179], v[158:159], v[100:101]
	s_waitcnt vmcnt(2)
; __device__ __forceinline__ unsigned pk2(float lo, float hi) { const f32x2c_t v = {lo, hi}; return __builtin_bit_cast(unsigned, __builtin_convertvector(v, bf16x2c_t)); }
;     __device__ __forceinline__ void operator()(const f32x4 (&acc)[2][2][4][2], const Unit& u, int wr, int wc, int fr, int fq) const {
;     ...
;             for (int ai = 0; ai < 2; ++ai)
; #pragma unroll
;                 for (int m = 0; m < 4; ++m) {
;                     const int l = lbase + 128 * ai + 16 * m; const float rsv = rs[b * 2048 + l] * qs;
;                     unsigned wl[4], wh[4];
; #pragma unroll
;                     for (int n = 0; n < 2; ++n) {
;                         const f32x4 c4 = *(const f32x4*)(cosT + l * 32 + 8 * fq + 4 * n), s4 = *(const f32x4*)(sinT + l * 32 + 8 * fq + 4 * n);
;                         const f32x4 t1 = acc[ai][0][m][n] * rsv, t2 = acc[ai][1][m][n] * rsv;
;                         const f32x4 lo = t1 * c4 - t2 * s4, hi = t2 * c4 + t1 * s4;
;                         wl[2 * n] = pk2(lo[0], lo[1]); wl[2 * n + 1] = pk2(lo[2], lo[3]); wh[2 * n] = pk2(hi[0], hi[1]); wh[2 * n + 1] = pk2(hi[2], hi[3]);
;                         cl[n] += lo; ch[n] += hi;
;                     }
;                     bf16_t* o = obase + (unsigned)l * 64u;
;                     *(u32x4*)o = (u32x4){wl[0], wl[1], wl[2], wl[3]};
;                     *(u32x4*)(o + 32) = (u32x4){wh[0], wh[1], wh[2], wh[3]};
;                 }
	v_pk_mul_f32 v[180:181], v[164:165], v[98:99]
	v_pk_mul_f32 v[98:99], v[166:167], v[100:101]
	v_pk_fma_f32 v[108:109], v[154:155], v[112:113], v[108:109] neg_lo:[0,0,1] neg_hi:[0,0,1]
	v_pk_fma_f32 v[110:111], v[152:153], v[170:171], v[106:107] neg_lo:[0,0,1] neg_hi:[0,0,1]
	v_pk_fma_f32 v[106:107], v[150:151], v[112:113], v[104:105]
	v_pk_fma_f32 v[112:113], v[148:149], v[170:171], v[102:103]
	v_pk_fma_f32 v[100:101], v[166:167], v[174:175], v[178:179] neg_lo:[0,0,1] neg_hi:[0,0,1]
	v_pk_fma_f32 v[102:103], v[164:165], v[172:173], v[176:177] neg_lo:[0,0,1] neg_hi:[0,0,1]
	v_pk_fma_f32 v[98:99], v[158:159], v[174:175], v[98:99]
	v_pk_fma_f32 v[104:105], v[156:157], v[172:173], v[180:181]
	v_cvt_pk_bf16_f32 v226, v110, v111
	v_cvt_pk_bf16_f32 v227, v108, v109
	v_cvt_pk_bf16_f32 v228, v102, v103
	v_cvt_pk_bf16_f32 v229, v100, v101
	v_cvt_pk_bf16_f32 v230, v112, v113
	v_cvt_pk_bf16_f32 v231, v106, v107
	v_cvt_pk_bf16_f32 v232, v104, v105
	v_cvt_pk_bf16_f32 v233, v98, v99
	v_mov_b64_e32 v[236:237], v[160:161]
	global_load_dword v147, v[168:169], off
	v_mov_b32_e32 v149, v131
	v_lshlrev_b32_e32 v148, 5, v182
	v_lshlrev_b64 v[152:153], 2, v[148:149]
	v_lshl_add_u64 v[156:157], v[134:135], 0, v[152:153]
	global_load_dwordx4 v[148:151], v[156:157], off
	v_lshl_add_u64 v[160:161], v[132:133], 0, v[152:153]
	global_load_dwordx4 v[152:155], v[160:161], off
	s_nop 0
	global_load_dwordx4 v[156:159], v[156:157], off offset:16
	s_nop 0
	global_load_dwordx4 v[164:167], v[160:161], off offset:16
	global_store_dwordx4 v[236:237], v[226:229], off
	global_store_dwordx4 v[236:237], v[230:233], off offset:64
	v_mov_b32_e32 v161, v131
	v_lshlrev_b32_e32 v160, 6, v182
	v_add_u32_e32 v168, s39, v183
	v_lshl_add_u64 v[160:161], v[160:161], 1, v[144:145]
	v_ashrrev_i32_e32 v169, 31, v168
	v_lshl_add_u64 v[168:169], v[168:169], 2, s[20:21]
	v_add_u32_e32 v182, 0x80, v203
	s_waitcnt vmcnt(6)
	v_mul_f32_e32 v162, v146, v147
	v_pk_mul_f32 v[88:89], v[88:89], v[162:163] op_sel_hi:[1,0]
	v_pk_mul_f32 v[86:87], v[86:87], v[162:163] op_sel_hi:[1,0]
	v_pk_mul_f32 v[84:85], v[84:85], v[162:163] op_sel_hi:[1,0]
	v_pk_mul_f32 v[82:83], v[82:83], v[162:163] op_sel_hi:[1,0]
	v_pk_mul_f32 v[170:171], v[94:95], v[162:163] op_sel_hi:[1,0]
	v_pk_mul_f32 v[96:97], v[96:97], v[162:163] op_sel_hi:[1,0]
	v_pk_mul_f32 v[172:173], v[90:91], v[162:163] op_sel_hi:[1,0]
	v_pk_mul_f32 v[174:175], v[92:93], v[162:163] op_sel_hi:[1,0]
	s_waitcnt vmcnt(5)
	v_pk_mul_f32 v[90:91], v[148:149], v[86:87]
	v_pk_mul_f32 v[92:93], v[150:151], v[88:89]
	s_waitcnt vmcnt(4)
	v_pk_mul_f32 v[86:87], v[152:153], v[86:87]
	v_pk_mul_f32 v[88:89], v[154:155], v[88:89]
	s_waitcnt vmcnt(3)
	v_pk_mul_f32 v[176:177], v[156:157], v[82:83]
	v_pk_mul_f32 v[178:179], v[158:159], v[84:85]
	s_waitcnt vmcnt(2)
	v_pk_mul_f32 v[180:181], v[164:165], v[82:83]
	v_pk_mul_f32 v[82:83], v[166:167], v[84:85]
	v_pk_fma_f32 v[92:93], v[154:155], v[96:97], v[92:93] neg_lo:[0,0,1] neg_hi:[0,0,1]
	v_pk_fma_f32 v[94:95], v[152:153], v[170:171], v[90:91] neg_lo:[0,0,1] neg_hi:[0,0,1]
	v_pk_fma_f32 v[90:91], v[150:151], v[96:97], v[88:89]
	v_pk_fma_f32 v[96:97], v[148:149], v[170:171], v[86:87]
	v_pk_fma_f32 v[84:85], v[166:167], v[174:175], v[178:179] neg_lo:[0,0,1] neg_hi:[0,0,1]
	v_pk_fma_f32 v[86:87], v[164:165], v[172:173], v[176:177] neg_lo:[0,0,1] neg_hi:[0,0,1]
	v_pk_fma_f32 v[82:83], v[158:159], v[174:175], v[82:83]
	v_pk_fma_f32 v[88:89], v[156:157], v[172:173], v[180:181]
	v_cvt_pk_bf16_f32 v218, v94, v95
	v_cvt_pk_bf16_f32 v219, v92, v93
	v_cvt_pk_bf16_f32 v220, v86, v87
	v_cvt_pk_bf16_f32 v221, v84, v85
	v_cvt_pk_bf16_f32 v222, v96, v97
	v_cvt_pk_bf16_f32 v223, v90, v91
	v_cvt_pk_bf16_f32 v224, v88, v89
	v_cvt_pk_bf16_f32 v225, v82, v83
	v_mov_b64_e32 v[234:235], v[160:161]
	global_load_dword v147, v[168:169], off
	v_mov_b32_e32 v149, v131
	v_lshlrev_b32_e32 v148, 5, v183
	v_lshlrev_b64 v[152:153], 2, v[148:149]
	v_lshl_add_u64 v[156:157], v[134:135], 0, v[152:153]
	global_load_dwordx4 v[148:151], v[156:157], off
	v_lshl_add_u64 v[160:161], v[132:133], 0, v[152:153]
	global_load_dwordx4 v[152:155], v[160:161], off
	s_nop 0
	global_load_dwordx4 v[156:159], v[156:157], off offset:16
	s_nop 0
	global_load_dwordx4 v[164:167], v[160:161], off offset:16
	global_store_dwordx4 v[234:235], v[218:221], off
	global_store_dwordx4 v[234:235], v[222:225], off offset:64
	v_mov_b32_e32 v161, v131
	v_lshlrev_b32_e32 v160, 6, v183
	v_add_u32_e32 v168, s39, v182
	v_lshl_add_u64 v[160:161], v[160:161], 1, v[144:145]
	v_ashrrev_i32_e32 v169, 31, v168
	v_lshl_add_u64 v[168:169], v[168:169], 2, s[20:21]
	v_add_u32_e32 v183, 0x90, v203
	s_waitcnt vmcnt(6)
	v_mul_f32_e32 v162, v146, v147
	v_pk_mul_f32 v[72:73], v[72:73], v[162:163] op_sel_hi:[1,0]
	v_pk_mul_f32 v[70:71], v[70:71], v[162:163] op_sel_hi:[1,0]
	v_pk_mul_f32 v[68:69], v[68:69], v[162:163] op_sel_hi:[1,0]
	v_pk_mul_f32 v[66:67], v[66:67], v[162:163] op_sel_hi:[1,0]
	v_pk_mul_f32 v[170:171], v[78:79], v[162:163] op_sel_hi:[1,0]
	v_pk_mul_f32 v[80:81], v[80:81], v[162:163] op_sel_hi:[1,0]
	v_pk_mul_f32 v[172:173], v[74:75], v[162:163] op_sel_hi:[1,0]
	v_pk_mul_f32 v[174:175], v[76:77], v[162:163] op_sel_hi:[1,0]
	s_waitcnt vmcnt(5)
	v_pk_mul_f32 v[76:77], v[148:149], v[70:71]
	v_pk_mul_f32 v[74:75], v[150:151], v[72:73]
	s_waitcnt vmcnt(4)
	v_pk_mul_f32 v[70:71], v[152:153], v[70:71]
	v_pk_mul_f32 v[72:73], v[154:155], v[72:73]
	s_waitcnt vmcnt(3)
	v_pk_mul_f32 v[176:177], v[156:157], v[66:67]
	v_pk_mul_f32 v[178:179], v[158:159], v[68:69]
	s_waitcnt vmcnt(2)
; __device__ __forceinline__ unsigned pk2(float lo, float hi) { const f32x2c_t v = {lo, hi}; return __builtin_bit_cast(unsigned, __builtin_convertvector(v, bf16x2c_t)); }
;     __device__ __forceinline__ void operator()(const f32x4 (&acc)[2][2][4][2], const Unit& u, int wr, int wc, int fr, int fq) const {
;     ...
;             for (int ai = 0; ai < 2; ++ai)
; #pragma unroll
;                 for (int m = 0; m < 4; ++m) {
;                     const int l = lbase + 128 * ai + 16 * m; const float rsv = rs[b * 2048 + l] * qs;
;                     unsigned wl[4], wh[4];
; #pragma unroll
;                     for (int n = 0; n < 2; ++n) {
;                         const f32x4 c4 = *(const f32x4*)(cosT + l * 32 + 8 * fq + 4 * n), s4 = *(const f32x4*)(sinT + l * 32 + 8 * fq + 4 * n);
;                         const f32x4 t1 = acc[ai][0][m][n] * rsv, t2 = acc[ai][1][m][n] * rsv;
;                         const f32x4 lo = t1 * c4 - t2 * s4, hi = t2 * c4 + t1 * s4;
;                         wl[2 * n] = pk2(lo[0], lo[1]); wl[2 * n + 1] = pk2(lo[2], lo[3]); wh[2 * n] = pk2(hi[0], hi[1]); wh[2 * n + 1] = pk2(hi[2], hi[3]);
;                         cl[n] += lo; ch[n] += hi;
;                     }
;                     bf16_t* o = obase + (unsigned)l * 64u;
;                     *(u32x4*)o = (u32x4){wl[0], wl[1], wl[2], wl[3]};
;                     *(u32x4*)(o + 32) = (u32x4){wh[0], wh[1], wh[2], wh[3]};
;                 }
	v_pk_mul_f32 v[180:181], v[164:165], v[66:67]
	v_pk_mul_f32 v[68:69], v[166:167], v[68:69]
	v_pk_fma_f32 v[74:75], v[154:155], v[80:81], v[74:75] neg_lo:[0,0,1] neg_hi:[0,0,1]
	v_pk_fma_f32 v[78:79], v[152:153], v[170:171], v[76:77] neg_lo:[0,0,1] neg_hi:[0,0,1]
	v_pk_fma_f32 v[76:77], v[150:151], v[80:81], v[72:73]
	v_pk_fma_f32 v[80:81], v[148:149], v[170:171], v[70:71]
	v_pk_fma_f32 v[66:67], v[166:167], v[174:175], v[178:179] neg_lo:[0,0,1] neg_hi:[0,0,1]
	v_pk_fma_f32 v[70:71], v[164:165], v[172:173], v[176:177] neg_lo:[0,0,1] neg_hi:[0,0,1]
	v_pk_fma_f32 v[68:69], v[158:159], v[174:175], v[68:69]
	v_pk_fma_f32 v[72:73], v[156:157], v[172:173], v[180:181]
	v_cvt_pk_bf16_f32 v226, v78, v79
	v_cvt_pk_bf16_f32 v227, v74, v75
	v_cvt_pk_bf16_f32 v228, v70, v71
	v_cvt_pk_bf16_f32 v229, v66, v67
	v_cvt_pk_bf16_f32 v230, v80, v81
	v_cvt_pk_bf16_f32 v231, v76, v77
	v_cvt_pk_bf16_f32 v232, v72, v73
	v_cvt_pk_bf16_f32 v233, v68, v69
	v_mov_b64_e32 v[236:237], v[160:161]
	global_load_dword v147, v[168:169], off
	v_mov_b32_e32 v149, v131
	v_lshlrev_b32_e32 v148, 5, v182
	v_lshlrev_b64 v[152:153], 2, v[148:149]
	v_lshl_add_u64 v[156:157], v[134:135], 0, v[152:153]
	global_load_dwordx4 v[148:151], v[156:157], off
	v_lshl_add_u64 v[160:161], v[132:133], 0, v[152:153]
	global_load_dwordx4 v[152:155], v[160:161], off
	s_nop 0
	global_load_dwordx4 v[156:159], v[156:157], off offset:16
	s_nop 0
	global_load_dwordx4 v[164:167], v[160:161], off offset:16
	global_store_dwordx4 v[236:237], v[226:229], off
	global_store_dwordx4 v[236:237], v[230:233], off offset:64
	v_mov_b32_e32 v161, v131
	v_lshlrev_b32_e32 v160, 6, v182
	v_add_u32_e32 v168, s39, v183
	v_lshl_add_u64 v[160:161], v[160:161], 1, v[144:145]
	v_ashrrev_i32_e32 v169, 31, v168
	v_lshl_add_u64 v[168:169], v[168:169], 2, s[20:21]
	v_add_u32_e32 v182, 0xa0, v203
	s_waitcnt vmcnt(6)
	v_mul_f32_e32 v162, v146, v147
	v_pk_mul_f32 v[56:57], v[56:57], v[162:163] op_sel_hi:[1,0]
	v_pk_mul_f32 v[54:55], v[54:55], v[162:163] op_sel_hi:[1,0]
	v_pk_mul_f32 v[52:53], v[52:53], v[162:163] op_sel_hi:[1,0]
	v_pk_mul_f32 v[50:51], v[50:51], v[162:163] op_sel_hi:[1,0]
	v_pk_mul_f32 v[170:171], v[62:63], v[162:163] op_sel_hi:[1,0]
	v_pk_mul_f32 v[64:65], v[64:65], v[162:163] op_sel_hi:[1,0]
	v_pk_mul_f32 v[172:173], v[58:59], v[162:163] op_sel_hi:[1,0]
	v_pk_mul_f32 v[174:175], v[60:61], v[162:163] op_sel_hi:[1,0]
	s_waitcnt vmcnt(5)
	v_pk_mul_f32 v[60:61], v[148:149], v[54:55]
	v_pk_mul_f32 v[58:59], v[150:151], v[56:57]
	s_waitcnt vmcnt(4)
	v_pk_mul_f32 v[54:55], v[152:153], v[54:55]
	v_pk_mul_f32 v[56:57], v[154:155], v[56:57]
	s_waitcnt vmcnt(3)
	v_pk_mul_f32 v[176:177], v[156:157], v[50:51]
	v_pk_mul_f32 v[178:179], v[158:159], v[52:53]
	s_waitcnt vmcnt(2)
	v_pk_mul_f32 v[180:181], v[164:165], v[50:51]
	v_pk_mul_f32 v[52:53], v[166:167], v[52:53]
	v_pk_fma_f32 v[58:59], v[154:155], v[64:65], v[58:59] neg_lo:[0,0,1] neg_hi:[0,0,1]
	v_pk_fma_f32 v[62:63], v[152:153], v[170:171], v[60:61] neg_lo:[0,0,1] neg_hi:[0,0,1]
	v_pk_fma_f32 v[60:61], v[150:151], v[64:65], v[56:57]
	v_pk_fma_f32 v[64:65], v[148:149], v[170:171], v[54:55]
	v_pk_fma_f32 v[50:51], v[166:167], v[174:175], v[178:179] neg_lo:[0,0,1] neg_hi:[0,0,1]
	v_pk_fma_f32 v[54:55], v[164:165], v[172:173], v[176:177] neg_lo:[0,0,1] neg_hi:[0,0,1]
	v_pk_fma_f32 v[52:53], v[158:159], v[174:175], v[52:53]
	v_pk_fma_f32 v[56:57], v[156:157], v[172:173], v[180:181]
	v_cvt_pk_bf16_f32 v218, v62, v63
	v_cvt_pk_bf16_f32 v219, v58, v59
	v_cvt_pk_bf16_f32 v220, v54, v55
	v_cvt_pk_bf16_f32 v221, v50, v51
	v_cvt_pk_bf16_f32 v222, v64, v65
	v_cvt_pk_bf16_f32 v223, v60, v61
	v_cvt_pk_bf16_f32 v224, v56, v57
	v_cvt_pk_bf16_f32 v225, v52, v53
	v_mov_b64_e32 v[234:235], v[160:161]
	global_load_dword v147, v[168:169], off
	v_mov_b32_e32 v149, v131
	v_lshlrev_b32_e32 v148, 5, v183
	v_lshlrev_b64 v[152:153], 2, v[148:149]
	v_lshl_add_u64 v[156:157], v[134:135], 0, v[152:153]
	global_load_dwordx4 v[148:151], v[156:157], off
	v_lshl_add_u64 v[160:161], v[132:133], 0, v[152:153]
	global_load_dwordx4 v[152:155], v[160:161], off
	s_nop 0
	global_load_dwordx4 v[156:159], v[156:157], off offset:16
	s_nop 0
	global_load_dwordx4 v[164:167], v[160:161], off offset:16
	global_store_dwordx4 v[234:235], v[218:221], off
	global_store_dwordx4 v[234:235], v[222:225], off offset:64
	v_mov_b32_e32 v161, v131
	v_lshlrev_b32_e32 v160, 6, v183
	v_add_u32_e32 v168, s39, v182
	v_lshl_add_u64 v[160:161], v[160:161], 1, v[144:145]
	v_ashrrev_i32_e32 v169, 31, v168
	v_lshl_add_u64 v[168:169], v[168:169], 2, s[20:21]
	v_add_u32_e32 v183, 0xb0, v203
	s_waitcnt vmcnt(6)
	v_mul_f32_e32 v162, v146, v147
	v_pk_mul_f32 v[40:41], v[40:41], v[162:163] op_sel_hi:[1,0]
	v_pk_mul_f32 v[38:39], v[38:39], v[162:163] op_sel_hi:[1,0]
	v_pk_mul_f32 v[36:37], v[36:37], v[162:163] op_sel_hi:[1,0]
	v_pk_mul_f32 v[34:35], v[34:35], v[162:163] op_sel_hi:[1,0]
	v_pk_mul_f32 v[170:171], v[46:47], v[162:163] op_sel_hi:[1,0]
	v_pk_mul_f32 v[48:49], v[48:49], v[162:163] op_sel_hi:[1,0]
	v_pk_mul_f32 v[172:173], v[42:43], v[162:163] op_sel_hi:[1,0]
	v_pk_mul_f32 v[174:175], v[44:45], v[162:163] op_sel_hi:[1,0]
	s_waitcnt vmcnt(5)
	v_pk_mul_f32 v[44:45], v[148:149], v[38:39]
	v_pk_mul_f32 v[42:43], v[150:151], v[40:41]
	s_waitcnt vmcnt(4)
	v_pk_mul_f32 v[38:39], v[152:153], v[38:39]
	v_pk_mul_f32 v[40:41], v[154:155], v[40:41]
	s_waitcnt vmcnt(3)
	v_pk_mul_f32 v[176:177], v[156:157], v[34:35]
	v_pk_mul_f32 v[178:179], v[158:159], v[36:37]
	s_waitcnt vmcnt(2)
; __device__ __forceinline__ unsigned pk2(float lo, float hi) { const f32x2c_t v = {lo, hi}; return __builtin_bit_cast(unsigned, __builtin_convertvector(v, bf16x2c_t)); }
;     __device__ __forceinline__ void operator()(const f32x4 (&acc)[2][2][4][2], const Unit& u, int wr, int wc, int fr, int fq) const {
;     ...
;             for (int ai = 0; ai < 2; ++ai)
; #pragma unroll
;                 for (int m = 0; m < 4; ++m) {
;                     const int l = lbase + 128 * ai + 16 * m; const float rsv = rs[b * 2048 + l] * qs;
;                     unsigned wl[4], wh[4];
; #pragma unroll
;                     for (int n = 0; n < 2; ++n) {
;                         const f32x4 c4 = *(const f32x4*)(cosT + l * 32 + 8 * fq + 4 * n), s4 = *(const f32x4*)(sinT + l * 32 + 8 * fq + 4 * n);
;                         const f32x4 t1 = acc[ai][0][m][n] * rsv, t2 = acc[ai][1][m][n] * rsv;
;                         const f32x4 lo = t1 * c4 - t2 * s4, hi = t2 * c4 + t1 * s4;
;                         wl[2 * n] = pk2(lo[0], lo[1]); wl[2 * n + 1] = pk2(lo[2], lo[3]); wh[2 * n] = pk2(hi[0], hi[1]); wh[2 * n + 1] = pk2(hi[2], hi[3]);
;                         cl[n] += lo; ch[n] += hi;
;                     }
;                     bf16_t* o = obase + (unsigned)l * 64u;
;                     *(u32x4*)o = (u32x4){wl[0], wl[1], wl[2], wl[3]};
;                     *(u32x4*)(o + 32) = (u32x4){wh[0], wh[1], wh[2], wh[3]};
;                 }
	v_pk_mul_f32 v[180:181], v[164:165], v[34:35]
	v_pk_mul_f32 v[36:37], v[166:167], v[36:37]
	v_pk_fma_f32 v[42:43], v[154:155], v[48:49], v[42:43] neg_lo:[0,0,1] neg_hi:[0,0,1]
	v_pk_fma_f32 v[46:47], v[152:153], v[170:171], v[44:45] neg_lo:[0,0,1] neg_hi:[0,0,1]
	v_pk_fma_f32 v[44:45], v[150:151], v[48:49], v[40:41]
	v_pk_fma_f32 v[48:49], v[148:149], v[170:171], v[38:39]
	v_pk_fma_f32 v[34:35], v[166:167], v[174:175], v[178:179] neg_lo:[0,0,1] neg_hi:[0,0,1]
	v_pk_fma_f32 v[38:39], v[164:165], v[172:173], v[176:177] neg_lo:[0,0,1] neg_hi:[0,0,1]
	v_pk_fma_f32 v[36:37], v[158:159], v[174:175], v[36:37]
	v_pk_fma_f32 v[40:41], v[156:157], v[172:173], v[180:181]
	v_cvt_pk_bf16_f32 v226, v46, v47
	v_cvt_pk_bf16_f32 v227, v42, v43
	v_cvt_pk_bf16_f32 v228, v38, v39
	v_cvt_pk_bf16_f32 v229, v34, v35
	v_cvt_pk_bf16_f32 v230, v48, v49
	v_cvt_pk_bf16_f32 v231, v44, v45
	v_cvt_pk_bf16_f32 v232, v40, v41
	v_cvt_pk_bf16_f32 v233, v36, v37
	v_mov_b64_e32 v[236:237], v[160:161]
	global_load_dword v147, v[168:169], off
	v_mov_b32_e32 v149, v131
	v_lshlrev_b32_e32 v148, 5, v182
	v_lshlrev_b64 v[152:153], 2, v[148:149]
	v_lshl_add_u64 v[156:157], v[134:135], 0, v[152:153]
	global_load_dwordx4 v[148:151], v[156:157], off
	v_lshl_add_u64 v[160:161], v[132:133], 0, v[152:153]
	global_load_dwordx4 v[152:155], v[160:161], off
	s_nop 0
	global_load_dwordx4 v[156:159], v[156:157], off offset:16
	s_nop 0
	global_load_dwordx4 v[164:167], v[160:161], off offset:16
	global_store_dwordx4 v[236:237], v[226:229], off
	global_store_dwordx4 v[236:237], v[230:233], off offset:64
	v_mov_b32_e32 v161, v131
	v_lshlrev_b32_e32 v160, 6, v182
	v_add_u32_e32 v168, s39, v183
	v_lshl_add_u64 v[160:161], v[160:161], 1, v[144:145]
	v_ashrrev_i32_e32 v169, 31, v168
	v_lshl_add_u64 v[168:169], v[168:169], 2, s[20:21]
	s_waitcnt vmcnt(6)
	v_mul_f32_e32 v162, v146, v147
	v_pk_mul_f32 v[24:25], v[24:25], v[162:163] op_sel_hi:[1,0]
	v_pk_mul_f32 v[22:23], v[22:23], v[162:163] op_sel_hi:[1,0]
	v_pk_mul_f32 v[20:21], v[20:21], v[162:163] op_sel_hi:[1,0]
	v_pk_mul_f32 v[18:19], v[18:19], v[162:163] op_sel_hi:[1,0]
	v_pk_mul_f32 v[170:171], v[30:31], v[162:163] op_sel_hi:[1,0]
	v_pk_mul_f32 v[32:33], v[32:33], v[162:163] op_sel_hi:[1,0]
	v_pk_mul_f32 v[172:173], v[26:27], v[162:163] op_sel_hi:[1,0]
	v_pk_mul_f32 v[174:175], v[28:29], v[162:163] op_sel_hi:[1,0]
	s_waitcnt vmcnt(5)
	v_pk_mul_f32 v[28:29], v[148:149], v[22:23]
	v_pk_mul_f32 v[26:27], v[150:151], v[24:25]
	s_waitcnt vmcnt(4)
	v_pk_mul_f32 v[22:23], v[152:153], v[22:23]
	v_pk_mul_f32 v[24:25], v[154:155], v[24:25]
	s_waitcnt vmcnt(3)
	v_pk_mul_f32 v[176:177], v[156:157], v[18:19]
	v_pk_mul_f32 v[178:179], v[158:159], v[20:21]
	s_waitcnt vmcnt(2)
	v_pk_mul_f32 v[180:181], v[164:165], v[18:19]
	v_pk_mul_f32 v[20:21], v[166:167], v[20:21]
	v_pk_fma_f32 v[26:27], v[154:155], v[32:33], v[26:27] neg_lo:[0,0,1] neg_hi:[0,0,1]
	v_pk_fma_f32 v[30:31], v[152:153], v[170:171], v[28:29] neg_lo:[0,0,1] neg_hi:[0,0,1]
	v_pk_fma_f32 v[28:29], v[150:151], v[32:33], v[24:25]
	v_pk_fma_f32 v[32:33], v[148:149], v[170:171], v[22:23]
	v_pk_fma_f32 v[18:19], v[166:167], v[174:175], v[178:179] neg_lo:[0,0,1] neg_hi:[0,0,1]
	v_pk_fma_f32 v[22:23], v[164:165], v[172:173], v[176:177] neg_lo:[0,0,1] neg_hi:[0,0,1]
	v_pk_fma_f32 v[20:21], v[158:159], v[174:175], v[20:21]
	v_pk_fma_f32 v[24:25], v[156:157], v[172:173], v[180:181]
	v_cvt_pk_bf16_f32 v218, v30, v31
	v_cvt_pk_bf16_f32 v219, v26, v27
	v_cvt_pk_bf16_f32 v220, v22, v23
	v_cvt_pk_bf16_f32 v221, v18, v19
	v_cvt_pk_bf16_f32 v222, v32, v33
	v_cvt_pk_bf16_f32 v223, v28, v29
	v_cvt_pk_bf16_f32 v224, v24, v25
	v_cvt_pk_bf16_f32 v225, v20, v21
	v_mov_b64_e32 v[234:235], v[160:161]
	global_load_dword v147, v[168:169], off
	v_mov_b32_e32 v149, v131
	v_lshlrev_b32_e32 v148, 5, v183
	v_lshlrev_b64 v[152:153], 2, v[148:149]
	v_lshl_add_u64 v[156:157], v[134:135], 0, v[152:153]
	global_load_dwordx4 v[148:151], v[156:157], off
	v_lshl_add_u64 v[160:161], v[132:133], 0, v[152:153]
	global_load_dwordx4 v[152:155], v[160:161], off
	s_nop 0
	global_load_dwordx4 v[156:159], v[156:157], off offset:16
	s_nop 0
	global_load_dwordx4 v[164:167], v[160:161], off offset:16
	global_store_dwordx4 v[234:235], v[218:221], off
	global_store_dwordx4 v[234:235], v[222:225], off offset:64
	v_mov_b32_e32 v161, v131
	v_lshlrev_b32_e32 v160, 6, v183
	v_lshl_add_u64 v[160:161], v[160:161], 1, v[144:145]
	s_waitcnt vmcnt(6)
	v_mul_f32_e32 v144, v146, v147
	v_pk_mul_f32 v[8:9], v[8:9], v[144:145] op_sel_hi:[1,0]
	v_pk_mul_f32 v[6:7], v[6:7], v[144:145] op_sel_hi:[1,0]
	v_pk_mul_f32 v[4:5], v[4:5], v[144:145] op_sel_hi:[1,0]
	v_pk_mul_f32 v[2:3], v[2:3], v[144:145] op_sel_hi:[1,0]
	v_pk_mul_f32 v[146:147], v[14:15], v[144:145] op_sel_hi:[1,0]
	v_pk_mul_f32 v[14:15], v[16:17], v[144:145] op_sel_hi:[1,0]
	v_pk_mul_f32 v[168:169], v[10:11], v[144:145] op_sel_hi:[1,0]
	v_pk_mul_f32 v[170:171], v[12:13], v[144:145] op_sel_hi:[1,0]
	s_waitcnt vmcnt(5)
	v_pk_mul_f32 v[10:11], v[148:149], v[6:7]
	v_pk_mul_f32 v[12:13], v[150:151], v[8:9]
	s_waitcnt vmcnt(3)
	v_pk_mul_f32 v[144:145], v[156:157], v[2:3]
	v_pk_mul_f32 v[172:173], v[158:159], v[4:5]
	v_pk_mul_f32 v[16:17], v[152:153], v[6:7]
	v_pk_mul_f32 v[8:9], v[154:155], v[8:9]
	s_waitcnt vmcnt(2)
	v_pk_mul_f32 v[174:175], v[164:165], v[2:3]
	v_pk_mul_f32 v[4:5], v[166:167], v[4:5]
	v_pk_fma_f32 v[12:13], v[154:155], v[14:15], v[12:13] neg_lo:[0,0,1] neg_hi:[0,0,1]
	v_pk_fma_f32 v[6:7], v[152:153], v[146:147], v[10:11] neg_lo:[0,0,1] neg_hi:[0,0,1]
	v_pk_fma_f32 v[2:3], v[166:167], v[170:171], v[172:173] neg_lo:[0,0,1] neg_hi:[0,0,1]
	v_pk_fma_f32 v[10:11], v[164:165], v[168:169], v[144:145] neg_lo:[0,0,1] neg_hi:[0,0,1]
	v_pk_fma_f32 v[14:15], v[150:151], v[14:15], v[8:9]
	v_pk_fma_f32 v[16:17], v[148:149], v[146:147], v[16:17]
	v_pk_fma_f32 v[4:5], v[158:159], v[170:171], v[4:5]
	v_pk_fma_f32 v[8:9], v[156:157], v[168:169], v[174:175]
	v_cvt_pk_bf16_f32 v144, v6, v7
	v_cvt_pk_bf16_f32 v145, v12, v13
	v_cvt_pk_bf16_f32 v146, v10, v11
	v_cvt_pk_bf16_f32 v147, v2, v3
	v_cvt_pk_bf16_f32 v148, v16, v17
	v_cvt_pk_bf16_f32 v149, v14, v15
	v_cvt_pk_bf16_f32 v150, v8, v9
	v_cvt_pk_bf16_f32 v151, v4, v5
	global_store_dwordx4 v[160:161], v[144:147], off
	global_store_dwordx4 v[160:161], v[148:151], off offset:64
	s_cbranch_scc1 .LBB0_225
;     __device__ __forceinline__ void operator()(const f32x4 (&acc)[2][2][4][2], const Unit& u, int wr, int wc, int fr, int fq) const {
;     ...
;             if (seg == 1) {
; #pragma unroll
;                 for (int n = 0; n < 2; ++n)
; #pragma unroll
;                     for (int i = 0; i < 4; ++i) {
;                         float v = cl[n][i], v2 = ch[n][i];
;                         v += __shfl_xor(v, 1); v += __shfl_xor(v, 2); v += __shfl_xor(v, 4); v += __shfl_xor(v, 8);
;                         v2 += __shfl_xor(v2, 1); v2 += __shfl_xor(v2, 2); v2 += __shfl_xor(v2, 4); v2 += __shfl_xor(v2, 8);
;                         if (fr == 0) { float* kp = KSUM + ((b * 8 + head) * 8 + blk) * 64 + 8 * fq + 4 * n + i; atomicAdd(kp, v); atomicAdd(kp + 32, v2); }
;                     }
	v_pk_add_f32 v[126:127], v[126:127], 0 op_sel_hi:[1,0]
	v_pk_add_f32 v[128:129], v[128:129], 0 op_sel_hi:[1,0]
	v_pk_add_f32 v[110:111], v[126:127], v[110:111]
	v_pk_add_f32 v[112:113], v[128:129], v[112:113]
	v_pk_add_f32 v[94:95], v[110:111], v[94:95]
	v_pk_add_f32 v[96:97], v[112:113], v[96:97]
	v_pk_add_f32 v[78:79], v[94:95], v[78:79]
	v_pk_add_f32 v[80:81], v[96:97], v[80:81]
	v_pk_add_f32 v[62:63], v[78:79], v[62:63]
	v_pk_add_f32 v[64:65], v[80:81], v[64:65]
	v_pk_add_f32 v[46:47], v[62:63], v[46:47]
	v_pk_add_f32 v[48:49], v[64:65], v[48:49]
	v_pk_add_f32 v[30:31], v[46:47], v[30:31]
	v_pk_add_f32 v[32:33], v[48:49], v[32:33]
	v_pk_add_f32 v[30:31], v[30:31], v[6:7]
	v_and_b32_e32 v7, 64, v202
	v_xor_b32_e32 v6, 1, v202
	v_add_u32_e32 v7, 64, v7
	v_cmp_lt_i32_e32 vcc, v6, v7
	v_pk_add_f32 v[16:17], v[32:33], v[16:17]
	s_lshl_b32 s29, s38, 9
	v_cndmask_b32_e32 v6, v202, v6, vcc
	v_lshlrev_b32_e32 v32, 2, v6
	ds_bpermute_b32 v47, v32, v30
	ds_bpermute_b32 v48, v32, v16
	v_xor_b32_e32 v6, 2, v202
	v_cmp_lt_i32_e32 vcc, v6, v7
	s_lshl_b32 s27, s27, 6
	s_waitcnt lgkmcnt(1)
	v_add_f32_e32 v30, v30, v47
	v_cndmask_b32_e32 v6, v202, v6, vcc
	v_lshlrev_b32_e32 v33, 2, v6
	s_waitcnt lgkmcnt(0)
	v_add_f32_e32 v16, v16, v48
	ds_bpermute_b32 v47, v33, v30
	ds_bpermute_b32 v48, v33, v16
	v_xor_b32_e32 v6, 4, v202
	v_cmp_lt_i32_e32 vcc, v6, v7
	s_or_b32 s38, s29, s27
	s_ashr_i32 s39, s38, 31
	v_cndmask_b32_e32 v6, v202, v6, vcc
	v_lshlrev_b32_e32 v46, 2, v6
	v_xor_b32_e32 v6, 8, v202
	v_cmp_lt_i32_e32 vcc, v6, v7
	s_waitcnt lgkmcnt(1)
	v_add_f32_e32 v7, v30, v47
	s_waitcnt lgkmcnt(0)
	v_add_f32_e32 v48, v16, v48
	ds_bpermute_b32 v30, v46, v7
	ds_bpermute_b32 v49, v46, v48
	v_cndmask_b32_e32 v6, v202, v6, vcc
	v_lshlrev_b32_e32 v16, 2, v6
	s_waitcnt lgkmcnt(1)
	v_add_f32_e32 v30, v7, v30
	s_waitcnt lgkmcnt(0)
	v_add_f32_e32 v48, v48, v49
	ds_bpermute_b32 v47, v16, v30
	ds_bpermute_b32 v49, v16, v48
	v_lshl_add_u64 v[6:7], s[38:39], 2, v[136:137]
	s_and_saveexec_b64 s[38:39], s[4:5]
	s_cbranch_execz .LBB0_210
	s_waitcnt lgkmcnt(1)
	v_add_f32_e32 v30, v30, v47
	s_waitcnt lgkmcnt(0)
	v_add_f32_e32 v47, v48, v49
	global_atomic_add_f32 v[6:7], v30, off
	global_atomic_add_f32 v[6:7], v47, off offset:128
